# non-aligned GEMM epilogues (leading half starts its epilogue during the trailing half's last MFMA block; ALIGN barriers removed)
# baseline (speedup 1.0000x reference)
.LBB0_147:
	s_waitcnt vmcnt(0)
	v_readlane_b32 s71, v254, 10
	s_and_b64 vcc, exec, s[26:27]
	s_cbranch_vccz .Lna_1
	s_barrier
.Lna_1:
	s_barrier

.LBB0_221:
	ds_read_b128 v[88:91], v233
	ds_read_b128 v[92:95], v233 offset:1024
	ds_read_b128 v[112:115], v233 offset:2048
	ds_read_b128 v[116:119], v233 offset:3072
	ds_read_b128 v[132:135], v234
	ds_read_b128 v[136:139], v234 offset:1024
	ds_read_b128 v[152:155], v234 offset:2048
	ds_read_b128 v[156:159], v234 offset:3072
	s_add_u32 s52, s50, 0x100
	s_addc_u32 s53, s51, 0
	s_cmp_eq_u32 s97, 40
	s_cselect_b32 s57, s9, s53
	s_cselect_b32 s56, s8, s52
	s_cselect_b32 s55, s41, s96
	s_cselect_b32 s54, s40, s95
	v_lshl_add_u64 v[216:217], s[50:51], 0, v[196:197]
	s_add_i32 m0, s67, 0xc000
	ds_read_b128 v[160:163], v235
	ds_read_b128 v[164:167], v235 offset:1024
	ds_read_b128 v[168:171], v235 offset:2048
	ds_read_b128 v[172:175], v235 offset:3072
	ds_read_b128 v[176:179], v235 offset:4096
	ds_read_b128 v[180:183], v235 offset:5120
	ds_read_b128 v[208:211], v235 offset:6144
	ds_read_b128 v[212:215], v235 offset:7168
	global_load_lds_dwordx4 v[216:217], off
	v_lshl_add_u64 v[216:217], s[50:51], 0, v[198:199]
	s_add_i32 m0, s67, 0xe000
	s_nop 0
	global_load_lds_dwordx4 v[216:217], off
	s_waitcnt vmcnt(8)
	s_waitcnt lgkmcnt(0)
	s_setprio 1
	s_barrier
	v_mfma_f32_16x16x32_bf16 v[148:151], v[88:91], v[160:163], v[148:151]
	v_mfma_f32_16x16x32_bf16 v[144:147], v[112:115], v[160:163], v[144:147]
	v_mfma_f32_16x16x32_bf16 v[124:127], v[88:91], v[168:171], v[124:127]
	v_mfma_f32_16x16x32_bf16 v[120:123], v[112:115], v[168:171], v[120:123]
	v_mfma_f32_16x16x32_bf16 v[100:103], v[88:91], v[176:179], v[100:103]
	v_mfma_f32_16x16x32_bf16 v[96:99], v[112:115], v[176:179], v[96:99]
	v_mfma_f32_16x16x32_bf16 v[76:79], v[88:91], v[208:211], v[76:79]
	v_mfma_f32_16x16x32_bf16 v[72:75], v[112:115], v[208:211], v[72:75]
	v_mfma_f32_16x16x32_bf16 v[148:151], v[92:95], v[164:167], v[148:151]
	v_mfma_f32_16x16x32_bf16 v[144:147], v[116:119], v[164:167], v[144:147]
	v_mfma_f32_16x16x32_bf16 v[124:127], v[92:95], v[172:175], v[124:127]
	v_mfma_f32_16x16x32_bf16 v[120:123], v[116:119], v[172:175], v[120:123]
	v_mfma_f32_16x16x32_bf16 v[100:103], v[92:95], v[180:183], v[100:103]
	v_mfma_f32_16x16x32_bf16 v[96:99], v[116:119], v[180:183], v[96:99]
	v_mfma_f32_16x16x32_bf16 v[76:79], v[92:95], v[212:215], v[76:79]
	v_mfma_f32_16x16x32_bf16 v[72:75], v[116:119], v[212:215], v[72:75]
	v_mfma_f32_16x16x32_bf16 v[140:143], v[132:135], v[160:163], v[140:143]
	v_mfma_f32_16x16x32_bf16 v[128:131], v[152:155], v[160:163], v[128:131]
	v_mfma_f32_16x16x32_bf16 v[108:111], v[132:135], v[168:171], v[108:111]
	v_mfma_f32_16x16x32_bf16 v[104:107], v[152:155], v[168:171], v[104:107]
	v_mfma_f32_16x16x32_bf16 v[84:87], v[132:135], v[176:179], v[84:87]
	v_mfma_f32_16x16x32_bf16 v[80:83], v[152:155], v[176:179], v[80:83]
	v_mfma_f32_16x16x32_bf16 v[68:71], v[132:135], v[208:211], v[68:71]
	v_mfma_f32_16x16x32_bf16 v[64:67], v[152:155], v[208:211], v[64:67]
	v_mfma_f32_16x16x32_bf16 v[140:143], v[136:139], v[164:167], v[140:143]
	v_mfma_f32_16x16x32_bf16 v[128:131], v[156:159], v[164:167], v[128:131]
	v_mfma_f32_16x16x32_bf16 v[108:111], v[136:139], v[172:175], v[108:111]
	v_mfma_f32_16x16x32_bf16 v[104:107], v[156:159], v[172:175], v[104:107]
	v_mfma_f32_16x16x32_bf16 v[84:87], v[136:139], v[180:183], v[84:87]
	v_mfma_f32_16x16x32_bf16 v[80:83], v[156:159], v[180:183], v[80:83]
	v_mfma_f32_16x16x32_bf16 v[68:71], v[136:139], v[212:215], v[68:71]
	v_mfma_f32_16x16x32_bf16 v[64:67], v[156:159], v[212:215], v[64:67]
	s_barrier
	s_setprio 0
	s_add_i32 s50, s82, s66
	v_lshl_add_u64 v[216:217], s[54:55], 0, v[186:187]
	s_mov_b32 m0, s50
	ds_read_b128 v[160:163], v235 offset:16384
	ds_read_b128 v[164:167], v235 offset:17408
	ds_read_b128 v[168:171], v235 offset:18432
	ds_read_b128 v[172:175], v235 offset:19456
	ds_read_b128 v[176:179], v235 offset:20480
	ds_read_b128 v[180:183], v235 offset:21504
	ds_read_b128 v[208:211], v235 offset:22528
	ds_read_b128 v[212:215], v235 offset:23552
	global_load_lds_dwordx4 v[216:217], off
	s_add_i32 m0, s50, 0x2000
	s_add_u32 s50, s54, 0xb0000
	v_lshl_add_u64 v[218:219], s[54:55], 0, v[190:191]
	s_addc_u32 s51, s55, 0
	s_add_i32 vcc_lo, s85, s66
	global_load_lds_dwordx4 v[218:219], off
	v_lshl_add_u64 v[220:221], s[50:51], 0, v[186:187]
	s_mov_b32 m0, vcc_lo
	v_lshl_add_u64 v[222:223], s[56:57], 0, v[188:189]
	global_load_lds_dwordx4 v[220:221], off
	v_lshl_add_u64 v[220:221], s[50:51], 0, v[190:191]
	s_add_i32 m0, vcc_lo, 0x2000
	s_nop 0
	global_load_lds_dwordx4 v[220:221], off
	v_lshl_add_u64 v[220:221], s[56:57], 0, v[184:185]
	s_mov_b32 m0, s67
	s_nop 0
	global_load_lds_dwordx4 v[220:221], off
	s_mov_b32 m0, s68
	s_nop 0
	global_load_lds_dwordx4 v[222:223], off
	s_waitcnt vmcnt(8)
	s_waitcnt lgkmcnt(0)
	s_setprio 1
	s_barrier
	v_mfma_f32_16x16x32_bf16 v[60:63], v[88:91], v[160:163], v[60:63]
	v_mfma_f32_16x16x32_bf16 v[56:59], v[112:115], v[160:163], v[56:59]
	v_mfma_f32_16x16x32_bf16 v[44:47], v[88:91], v[168:171], v[44:47]
	v_mfma_f32_16x16x32_bf16 v[40:43], v[112:115], v[168:171], v[40:43]
	v_mfma_f32_16x16x32_bf16 v[28:31], v[88:91], v[176:179], v[28:31]
	v_mfma_f32_16x16x32_bf16 v[24:27], v[112:115], v[176:179], v[24:27]
	v_mfma_f32_16x16x32_bf16 v[12:15], v[88:91], v[208:211], v[12:15]
	v_mfma_f32_16x16x32_bf16 v[8:11], v[112:115], v[208:211], v[8:11]
	v_mfma_f32_16x16x32_bf16 v[60:63], v[92:95], v[164:167], v[60:63]
	v_mfma_f32_16x16x32_bf16 v[56:59], v[116:119], v[164:167], v[56:59]
	v_mfma_f32_16x16x32_bf16 v[44:47], v[92:95], v[172:175], v[44:47]
	v_mfma_f32_16x16x32_bf16 v[40:43], v[116:119], v[172:175], v[40:43]
	v_mfma_f32_16x16x32_bf16 v[28:31], v[92:95], v[180:183], v[28:31]
	v_mfma_f32_16x16x32_bf16 v[24:27], v[116:119], v[180:183], v[24:27]
	v_mfma_f32_16x16x32_bf16 v[12:15], v[92:95], v[212:215], v[12:15]
	v_mfma_f32_16x16x32_bf16 v[8:11], v[116:119], v[212:215], v[8:11]
	v_mfma_f32_16x16x32_bf16 v[52:55], v[132:135], v[160:163], v[52:55]
	v_mfma_f32_16x16x32_bf16 v[48:51], v[152:155], v[160:163], v[48:51]
	v_mfma_f32_16x16x32_bf16 v[36:39], v[132:135], v[168:171], v[36:39]
	v_mfma_f32_16x16x32_bf16 v[32:35], v[152:155], v[168:171], v[32:35]
	v_mfma_f32_16x16x32_bf16 v[20:23], v[132:135], v[176:179], v[20:23]
	v_mfma_f32_16x16x32_bf16 v[16:19], v[152:155], v[176:179], v[16:19]
	v_mfma_f32_16x16x32_bf16 v[4:7], v[132:135], v[208:211], v[4:7]
	v_mfma_f32_16x16x32_bf16 v[0:3], v[152:155], v[208:211], v[0:3]
	v_mfma_f32_16x16x32_bf16 v[52:55], v[136:139], v[164:167], v[52:55]
	v_mfma_f32_16x16x32_bf16 v[48:51], v[156:159], v[164:167], v[48:51]
	v_mfma_f32_16x16x32_bf16 v[36:39], v[136:139], v[172:175], v[36:39]
	v_mfma_f32_16x16x32_bf16 v[32:35], v[156:159], v[172:175], v[32:35]
	v_mfma_f32_16x16x32_bf16 v[20:23], v[136:139], v[180:183], v[20:23]
	v_mfma_f32_16x16x32_bf16 v[16:19], v[156:159], v[180:183], v[16:19]
	v_mfma_f32_16x16x32_bf16 v[4:7], v[136:139], v[212:215], v[4:7]
	v_mfma_f32_16x16x32_bf16 v[0:3], v[156:159], v[212:215], v[0:3]
	s_barrier
	s_setprio 0
	s_add_i32 vcc_lo, 0, 0x18000
	s_add_i32 vcc_hi, 0, 0x1c000
	v_add_u32_e32 v116, vcc_lo, v230
	v_add_u32_e32 v156, vcc_hi, v230
	ds_read_b128 v[88:91], v116
	ds_read_b128 v[92:95], v116 offset:1024
	ds_read_b128 v[112:115], v116 offset:2048
	ds_read_b128 v[116:119], v116 offset:3072
	ds_read_b128 v[132:135], v156
	ds_read_b128 v[136:139], v156 offset:1024
	ds_read_b128 v[152:155], v156 offset:2048
	ds_read_b128 v[156:159], v156 offset:3072
	s_add_u32 s50, s56, 0xb0000
	s_addc_u32 s51, s57, 0
	s_mov_b32 m0, s69
	v_lshl_add_u64 v[224:225], s[50:51], 0, v[184:185]
	ds_read_b128 v[160:163], v235 offset:32768
	ds_read_b128 v[164:167], v235 offset:33792
	ds_read_b128 v[168:171], v235 offset:34816
	ds_read_b128 v[172:175], v235 offset:35840
	ds_read_b128 v[176:179], v235 offset:36864
	ds_read_b128 v[180:183], v235 offset:37888
	ds_read_b128 v[208:211], v235 offset:38912
	ds_read_b128 v[212:215], v235 offset:39936
	global_load_lds_dwordx4 v[224:225], off
	v_lshl_add_u64 v[224:225], s[50:51], 0, v[188:189]
	s_mov_b32 m0, s70
	s_nop 0
	global_load_lds_dwordx4 v[224:225], off
	s_waitcnt vmcnt(8)
	s_waitcnt lgkmcnt(0)
	s_setprio 1
	s_barrier
	v_mfma_f32_16x16x32_bf16 v[148:151], v[88:91], v[160:163], v[148:151]
	v_mfma_f32_16x16x32_bf16 v[144:147], v[112:115], v[160:163], v[144:147]
	v_mfma_f32_16x16x32_bf16 v[124:127], v[88:91], v[168:171], v[124:127]
	v_mfma_f32_16x16x32_bf16 v[120:123], v[112:115], v[168:171], v[120:123]
	v_mfma_f32_16x16x32_bf16 v[100:103], v[88:91], v[176:179], v[100:103]
	v_mfma_f32_16x16x32_bf16 v[96:99], v[112:115], v[176:179], v[96:99]
	v_mfma_f32_16x16x32_bf16 v[76:79], v[88:91], v[208:211], v[76:79]
	v_mfma_f32_16x16x32_bf16 v[72:75], v[112:115], v[208:211], v[72:75]
	v_mfma_f32_16x16x32_bf16 v[148:151], v[92:95], v[164:167], v[148:151]
	v_mfma_f32_16x16x32_bf16 v[144:147], v[116:119], v[164:167], v[144:147]
	v_mfma_f32_16x16x32_bf16 v[124:127], v[92:95], v[172:175], v[124:127]
	v_mfma_f32_16x16x32_bf16 v[120:123], v[116:119], v[172:175], v[120:123]
	v_mfma_f32_16x16x32_bf16 v[100:103], v[92:95], v[180:183], v[100:103]
	v_mfma_f32_16x16x32_bf16 v[96:99], v[116:119], v[180:183], v[96:99]
	v_mfma_f32_16x16x32_bf16 v[76:79], v[92:95], v[212:215], v[76:79]
	v_mfma_f32_16x16x32_bf16 v[72:75], v[116:119], v[212:215], v[72:75]
	v_mfma_f32_16x16x32_bf16 v[140:143], v[132:135], v[160:163], v[140:143]
	v_mfma_f32_16x16x32_bf16 v[128:131], v[152:155], v[160:163], v[128:131]
	v_mfma_f32_16x16x32_bf16 v[108:111], v[132:135], v[168:171], v[108:111]
	v_mfma_f32_16x16x32_bf16 v[104:107], v[152:155], v[168:171], v[104:107]
	v_mfma_f32_16x16x32_bf16 v[84:87], v[132:135], v[176:179], v[84:87]
	v_mfma_f32_16x16x32_bf16 v[80:83], v[152:155], v[176:179], v[80:83]
	v_mfma_f32_16x16x32_bf16 v[68:71], v[132:135], v[208:211], v[68:71]
	v_mfma_f32_16x16x32_bf16 v[64:67], v[152:155], v[208:211], v[64:67]
	v_mfma_f32_16x16x32_bf16 v[140:143], v[136:139], v[164:167], v[140:143]
	v_mfma_f32_16x16x32_bf16 v[128:131], v[156:159], v[164:167], v[128:131]
	v_mfma_f32_16x16x32_bf16 v[108:111], v[136:139], v[172:175], v[108:111]
	v_mfma_f32_16x16x32_bf16 v[104:107], v[156:159], v[172:175], v[104:107]
	v_mfma_f32_16x16x32_bf16 v[84:87], v[136:139], v[180:183], v[84:87]
	v_mfma_f32_16x16x32_bf16 v[80:83], v[156:159], v[180:183], v[80:83]
	v_mfma_f32_16x16x32_bf16 v[68:71], v[136:139], v[212:215], v[68:71]
	v_mfma_f32_16x16x32_bf16 v[64:67], v[156:159], v[212:215], v[64:67]
	s_barrier
	s_setprio 0
	s_add_i32 s50, vcc_lo, s66
	v_lshl_add_u64 v[216:217], v[216:217], 0, s[46:47]
	s_mov_b32 m0, s50
	ds_read_b128 v[160:163], v235 offset:49152
	ds_read_b128 v[164:167], v235 offset:50176
	ds_read_b128 v[168:171], v235 offset:51200
	ds_read_b128 v[172:175], v235 offset:52224
	ds_read_b128 v[176:179], v235 offset:53248
	ds_read_b128 v[180:183], v235 offset:54272
	ds_read_b128 v[208:211], v235 offset:55296
	ds_read_b128 v[212:215], v235 offset:56320
	global_load_lds_dwordx4 v[216:217], off
	s_add_i32 m0, s50, 0x2000
	s_add_u32 s50, s54, 0xb0080
	v_lshl_add_u64 v[216:217], v[218:219], 0, s[46:47]
	s_addc_u32 s51, s55, 0
	s_add_i32 s54, vcc_hi, s66
	global_load_lds_dwordx4 v[216:217], off
	v_lshl_add_u64 v[216:217], s[50:51], 0, v[186:187]
	s_mov_b32 m0, s54
	s_nop 0
	global_load_lds_dwordx4 v[216:217], off
	v_lshl_add_u64 v[216:217], s[50:51], 0, v[190:191]
	s_add_i32 m0, s54, 0x2000
	s_nop 0
	global_load_lds_dwordx4 v[216:217], off
	v_lshl_add_u64 v[216:217], v[220:221], 0, s[46:47]
	s_mov_b32 m0, s74
	s_nop 0
	global_load_lds_dwordx4 v[216:217], off
	v_lshl_add_u64 v[216:217], v[222:223], 0, s[46:47]
	s_mov_b32 m0, s75
	s_nop 0
	global_load_lds_dwordx4 v[216:217], off
	s_waitcnt vmcnt(8)
	s_waitcnt lgkmcnt(0)
	s_setprio 1
	s_barrier
	v_mfma_f32_16x16x32_bf16 v[60:63], v[88:91], v[160:163], v[60:63]
	v_mfma_f32_16x16x32_bf16 v[56:59], v[112:115], v[160:163], v[56:59]
	v_mfma_f32_16x16x32_bf16 v[44:47], v[88:91], v[168:171], v[44:47]
	v_mfma_f32_16x16x32_bf16 v[40:43], v[112:115], v[168:171], v[40:43]
	v_mfma_f32_16x16x32_bf16 v[28:31], v[88:91], v[176:179], v[28:31]
	v_mfma_f32_16x16x32_bf16 v[24:27], v[112:115], v[176:179], v[24:27]
	v_mfma_f32_16x16x32_bf16 v[12:15], v[88:91], v[208:211], v[12:15]
	v_mfma_f32_16x16x32_bf16 v[8:11], v[112:115], v[208:211], v[8:11]
	v_mfma_f32_16x16x32_bf16 v[60:63], v[92:95], v[164:167], v[60:63]
	v_mfma_f32_16x16x32_bf16 v[56:59], v[116:119], v[164:167], v[56:59]
	v_mfma_f32_16x16x32_bf16 v[44:47], v[92:95], v[172:175], v[44:47]
	v_mfma_f32_16x16x32_bf16 v[40:43], v[116:119], v[172:175], v[40:43]
	v_mfma_f32_16x16x32_bf16 v[28:31], v[92:95], v[180:183], v[28:31]
	v_mfma_f32_16x16x32_bf16 v[24:27], v[116:119], v[180:183], v[24:27]
	v_mfma_f32_16x16x32_bf16 v[12:15], v[92:95], v[212:215], v[12:15]
	v_mfma_f32_16x16x32_bf16 v[8:11], v[116:119], v[212:215], v[8:11]
	v_mfma_f32_16x16x32_bf16 v[52:55], v[132:135], v[160:163], v[52:55]
	v_mfma_f32_16x16x32_bf16 v[48:51], v[152:155], v[160:163], v[48:51]
	v_mfma_f32_16x16x32_bf16 v[36:39], v[132:135], v[168:171], v[36:39]
	v_mfma_f32_16x16x32_bf16 v[32:35], v[152:155], v[168:171], v[32:35]
	v_mfma_f32_16x16x32_bf16 v[20:23], v[132:135], v[176:179], v[20:23]
	v_mfma_f32_16x16x32_bf16 v[16:19], v[152:155], v[176:179], v[16:19]
	v_mfma_f32_16x16x32_bf16 v[4:7], v[132:135], v[208:211], v[4:7]
	v_mfma_f32_16x16x32_bf16 v[0:3], v[152:155], v[208:211], v[0:3]
	v_mfma_f32_16x16x32_bf16 v[52:55], v[136:139], v[164:167], v[52:55]
	v_mfma_f32_16x16x32_bf16 v[48:51], v[156:159], v[164:167], v[48:51]
	v_mfma_f32_16x16x32_bf16 v[36:39], v[136:139], v[172:175], v[36:39]
	v_mfma_f32_16x16x32_bf16 v[32:35], v[156:159], v[172:175], v[32:35]
	v_mfma_f32_16x16x32_bf16 v[20:23], v[136:139], v[180:183], v[20:23]
	v_mfma_f32_16x16x32_bf16 v[16:19], v[156:159], v[180:183], v[16:19]
	v_mfma_f32_16x16x32_bf16 v[4:7], v[136:139], v[212:215], v[4:7]
	v_mfma_f32_16x16x32_bf16 v[0:3], v[156:159], v[212:215], v[0:3]
	s_barrier
	s_setprio 0
	s_add_i32 s97, s97, 2
	s_add_u32 s95, s95, 0x100
	s_addc_u32 s96, s96, 0
	s_cmp_gt_u32 s97, 41
	s_mov_b64 s[50:51], s[52:53]
	s_cbranch_scc0 .LBB0_221
	s_and_b64 vcc, exec, s[48:49]
	s_cbranch_vccz .LBB0_224
.LBB0_224:
	s_lshl_b32 s50, s36, 8
	s_or_b32 s50, s50, s78
	s_ashr_i32 s51, s50, 31
	v_lshl_add_u64 v[116:117], s[50:51], 2, v[194:195]
	s_lshl_b32 s52, s94, 8
	global_load_dwordx4 v[88:91], v[116:117], off
	global_load_dwordx4 v[92:95], v[116:117], off offset:16
	global_load_dwordx4 v[112:115], v[116:117], off offset:128
	s_add_i32 s52, s52, s73
	v_or_b32_e32 v208, s52, v229
	v_ashrrev_i32_e32 v209, 31, v208
	v_lshl_add_u64 v[132:133], v[208:209], 2, s[44:45]
	global_load_dword v154, v[132:133], off
	v_or_b32_e32 v134, 0x80, v229
	global_load_dwordx4 v[116:119], v[116:117], off offset:144
	s_ashr_i32 s53, s52, 31
	v_add_u32_e32 v134, s52, v134
	s_lshl_b64 s[52:53], s[52:53], 11
	s_add_u32 s52, s62, s52
	s_addc_u32 s53, s63, s53
	s_lshl_b64 s[50:51], s[50:51], 1
	s_add_u32 s50, s52, s50
	s_addc_u32 s51, s53, s51
	v_mov_b32_e32 v203, v193
	v_ashrrev_i32_e32 v135, 31, v134
	v_lshl_add_u64 v[218:219], s[50:51], 0, v[192:193]
	v_mov_b32_e32 v205, v193
	v_lshl_add_u64 v[134:135], v[134:135], 2, s[44:45]
	global_load_dword v242, v[132:133], off offset:64
	global_load_dword v241, v[132:133], off offset:128
	global_load_dword v240, v[132:133], off offset:192
	global_load_dword v239, v[134:135], off
	global_load_dword v238, v[134:135], off offset:64
	global_load_dword v237, v[134:135], off offset:128
	global_load_dword v236, v[134:135], off offset:192
	v_lshl_add_u64 v[132:133], v[218:219], 0, v[202:203]
	v_lshl_add_u64 v[252:253], v[132:133], 0, v[204:205]
	s_movk_i32 s50, 0x4000
	v_add_co_u32_e32 v132, vcc, s50, v252
	s_mov_b32 s50, 0xc000
	s_nop 0
	v_addc_co_u32_e32 v133, vcc, 0, v253, vcc
	global_load_dwordx4 v[244:247], v[252:253], off
	global_load_dwordx4 v[248:251], v[132:133], off
	v_add_co_u32_e32 v134, vcc, s77, v252
	v_mov_b32_e32 v207, v193
	s_nop 0
	v_addc_co_u32_e32 v135, vcc, 0, v253, vcc
	v_add_co_u32_e32 v136, vcc, s50, v252
	s_mov_b32 s50, 0x14000
	s_nop 0
	v_addc_co_u32_e32 v137, vcc, 0, v253, vcc
	v_add_co_u32_e32 v138, vcc, s71, v252
	v_lshl_add_u64 v[218:219], v[218:219], 0, v[206:207]
	s_nop 0
	v_addc_co_u32_e32 v139, vcc, 0, v253, vcc
	v_add_co_u32_e32 v132, vcc, s50, v252
	s_mov_b32 s50, 0x1c000
	s_nop 0
	v_addc_co_u32_e32 v133, vcc, 0, v253, vcc
	v_add_co_u32_e32 v152, vcc, s76, v252
	global_load_dwordx4 v[180:183], v[134:135], off
	global_load_dwordx4 v[176:179], v[136:137], off
	global_load_dwordx4 v[172:175], v[138:139], off
	global_load_dwordx4 v[168:171], v[132:133], off
	v_addc_co_u32_e32 v153, vcc, 0, v253, vcc
	v_mov_b32_e32 v243, v193
	v_lshl_add_u64 v[218:219], v[218:219], 0, v[204:205]
	s_waitcnt vmcnt(0)
	v_rcp_f32_e32 v224, v88
	v_add_co_u32_e32 v88, vcc, s50, v252
	v_rcp_f32_e32 v225, v89
	s_nop 0
	v_addc_co_u32_e32 v89, vcc, 0, v253, vcc
	global_load_dwordx4 v[164:167], v[152:153], off
	global_load_dwordx4 v[160:163], v[88:89], off
	v_add_co_u32_e32 v88, vcc, s87, v252
	s_mov_b32 s50, 0x44000
	s_nop 0
	v_addc_co_u32_e32 v89, vcc, 0, v253, vcc
	v_rcp_f32_e32 v226, v90
	v_add_co_u32_e32 v90, vcc, s50, v252
	v_rcp_f32_e32 v227, v91
	s_nop 0
	v_addc_co_u32_e32 v91, vcc, 0, v253, vcc
	v_rcp_f32_e32 v200, v154
	global_load_dwordx4 v[156:159], v[88:89], off
	global_load_dwordx4 v[152:155], v[90:91], off
	v_add_co_u32_e32 v88, vcc, s88, v252
	s_mov_b32 s50, 0x4c000
	s_nop 0
	v_addc_co_u32_e32 v89, vcc, 0, v253, vcc
	v_add_co_u32_e32 v90, vcc, s50, v252
	s_mov_b32 s50, 0x54000
	s_nop 0
	v_addc_co_u32_e32 v91, vcc, 0, v253, vcc
	global_load_dwordx4 v[136:139], v[88:89], off
	global_load_dwordx4 v[132:135], v[90:91], off
	v_add_co_u32_e32 v88, vcc, s89, v252
	v_rcp_f32_e32 v212, v112
	s_nop 0
	v_addc_co_u32_e32 v89, vcc, 0, v253, vcc
	v_add_co_u32_e32 v90, vcc, s50, v252
	v_rcp_f32_e32 v213, v113
	s_nop 0
	v_addc_co_u32_e32 v91, vcc, 0, v253, vcc
	v_rcp_f32_e32 v216, v114
	v_rcp_f32_e32 v217, v115
	v_rcp_f32_e32 v210, v116
	v_rcp_f32_e32 v211, v117
	v_rcp_f32_e32 v214, v118
	v_rcp_f32_e32 v215, v119
	global_load_dwordx4 v[116:119], v[88:89], off
	global_load_dwordx4 v[112:115], v[90:91], off
	v_add_co_u32_e32 v88, vcc, s90, v252
	s_mov_b32 s50, 0x5c000
	s_nop 0
	v_addc_co_u32_e32 v89, vcc, 0, v253, vcc
	v_add_co_u32_e32 v90, vcc, s50, v252
	v_rcp_f32_e32 v220, v92
	s_nop 0
	v_addc_co_u32_e32 v91, vcc, 0, v253, vcc
	v_rcp_f32_e32 v221, v93
	v_rcp_f32_e32 v222, v94
	v_rcp_f32_e32 v223, v95
	global_load_dwordx4 v[92:95], v[88:89], off
	s_nop 0
	global_load_dwordx4 v[88:91], v[90:91], off
	v_cndmask_b32_e64 v207, v244, v248, s[10:11]
	v_cndmask_b32_e64 v205, v245, v249, s[10:11]
	v_cndmask_b32_e64 v203, v246, v250, s[10:11]
	v_mov_b32_dpp v243, v207 row_ror:8 row_mask:0xf bank_mask:0xf
	v_mov_b32_e32 v207, v193
	v_cndmask_b32_e64 v201, v247, v251, s[10:11]
	s_lshl_b32 s50, s36, 2
	v_mov_b32_dpp v207, v205 row_ror:8 row_mask:0xf bank_mask:0xf
	v_mov_b32_e32 v205, v193
	s_ashr_i32 s51, s50, 31
	s_nop 0
	v_mov_b32_dpp v205, v203 row_ror:8 row_mask:0xf bank_mask:0xf
	v_mov_b32_e32 v203, v193
	v_cndmask_b32_e64 v252, v205, v246, s[10:11]
	v_cndmask_b32_e64 v205, v250, v205, s[10:11]
	v_mov_b32_dpp v203, v201 row_ror:8 row_mask:0xf bank_mask:0xf
	v_cndmask_b32_e64 v201, v203, v247, s[10:11]
	v_cndmask_b32_e64 v247, v207, v245, s[10:11]
	v_cndmask_b32_e64 v245, v243, v244, s[10:11]
	v_lshlrev_b32_e32 v244, 16, v245
	v_and_b32_e32 v245, 0xffff0000, v245
	v_lshlrev_b32_e32 v246, 16, v247
	v_and_b32_e32 v247, 0xffff0000, v247
	v_pk_mul_f32 v[244:245], v[224:225], v[244:245]
	v_cndmask_b32_e64 v203, v251, v203, s[10:11]
	v_cndmask_b32_e64 v207, v249, v207, s[10:11]
	v_cndmask_b32_e64 v243, v248, v243, s[10:11]
	v_lshlrev_b32_e32 v248, 16, v252
	v_and_b32_e32 v249, 0xffff0000, v252
	v_lshlrev_b32_e32 v250, 16, v201
	v_and_b32_e32 v251, 0xffff0000, v201
	v_pk_mul_f32 v[246:247], v[226:227], v[246:247]
	v_pk_mul_f32 v[244:245], v[200:201], v[244:245] op_sel_hi:[0,1]
	v_pk_mul_f32 v[246:247], v[200:201], v[246:247] op_sel_hi:[0,1]
	v_pk_mul_f32 v[250:251], v[222:223], v[250:251]
	v_pk_mul_f32 v[248:249], v[220:221], v[248:249]
	v_pk_fma_f32 v[148:149], v[148:149], 0.5, v[244:245] op_sel_hi:[1,0,1]
	v_pk_mul_f32 v[248:249], v[200:201], v[248:249] op_sel_hi:[0,1]
	v_pk_mul_f32 v[250:251], v[200:201], v[250:251] op_sel_hi:[0,1]
	v_pk_fma_f32 v[150:151], v[150:151], 0.5, v[246:247] op_sel_hi:[1,0,1]
	v_cvt_pk_bf16_f32 v201, v148, v149
	v_mul_f32_e32 v149, v149, v149
	v_pk_fma_f32 v[144:145], v[144:145], 0.5, v[248:249] op_sel_hi:[1,0,1]
	v_fmac_f32_e32 v149, v148, v148
	v_mul_f32_e32 v148, v151, v151
	v_cvt_pk_bf16_f32 v244, v150, v151
	v_cvt_pk_bf16_f32 v245, v144, v145
	v_fmac_f32_e32 v148, v150, v150
	v_mul_f32_e32 v145, v145, v145
	v_pk_fma_f32 v[146:147], v[146:147], 0.5, v[250:251] op_sel_hi:[1,0,1]
	v_add_f32_e32 v148, v149, v148
	v_fmac_f32_e32 v145, v144, v144
	v_add_f32_e32 v144, v145, v148
	v_mul_f32_e32 v145, v147, v147
	v_fmac_f32_e32 v145, v146, v146
	v_add_f32_e32 v247, v145, v144
	v_lshlrev_b32_e32 v144, 16, v243
	v_and_b32_e32 v145, 0xffff0000, v243
	v_cvt_pk_bf16_f32 v246, v146, v147
	v_lshlrev_b32_e32 v146, 16, v207
	v_and_b32_e32 v147, 0xffff0000, v207
	v_pk_mul_f32 v[144:145], v[212:213], v[144:145]
	v_lshlrev_b32_e32 v148, 16, v205
	v_and_b32_e32 v149, 0xffff0000, v205
	v_pk_mul_f32 v[146:147], v[216:217], v[146:147]
	v_pk_mul_f32 v[144:145], v[200:201], v[144:145] op_sel_hi:[0,1]
	v_pk_mul_f32 v[146:147], v[200:201], v[146:147] op_sel_hi:[0,1]
	v_pk_mul_f32 v[148:149], v[210:211], v[148:149]
	v_pk_fma_f32 v[140:141], v[140:141], 0.5, v[144:145] op_sel_hi:[1,0,1]
	v_lshlrev_b32_e32 v150, 16, v203
	v_and_b32_e32 v151, 0xffff0000, v203
	v_pk_mul_f32 v[148:149], v[200:201], v[148:149] op_sel_hi:[0,1]
	v_pk_fma_f32 v[142:143], v[142:143], 0.5, v[146:147] op_sel_hi:[1,0,1]
	v_cvt_pk_bf16_f32 v144, v140, v141
	v_mul_f32_e32 v141, v141, v141
	v_pk_mul_f32 v[150:151], v[214:215], v[150:151]
	v_pk_fma_f32 v[128:129], v[128:129], 0.5, v[148:149] op_sel_hi:[1,0,1]
	v_fmac_f32_e32 v141, v140, v140
	v_mul_f32_e32 v140, v143, v143
	v_pk_mul_f32 v[150:151], v[200:201], v[150:151] op_sel_hi:[0,1]
	v_cvt_pk_bf16_f32 v145, v142, v143
	v_cvt_pk_bf16_f32 v146, v128, v129
	v_fmac_f32_e32 v140, v142, v142
	v_mul_f32_e32 v129, v129, v129
	v_pk_fma_f32 v[130:131], v[130:131], 0.5, v[150:151] op_sel_hi:[1,0,1]
	v_add_f32_e32 v140, v141, v140
	v_fmac_f32_e32 v129, v128, v128
	v_add_f32_e32 v128, v129, v140
	v_mul_f32_e32 v129, v131, v131
	v_fmac_f32_e32 v129, v130, v130
	v_add_f32_e32 v128, v129, v128
	v_cvt_pk_bf16_f32 v147, v130, v131
	v_add_f32_e32 v148, v247, v128
	v_cndmask_b32_e64 v128, v246, v147, s[10:11]
	v_cndmask_b32_e64 v129, v245, v146, s[10:11]
	v_cndmask_b32_e64 v130, v244, v145, s[10:11]
	v_cndmask_b32_e64 v131, v201, v144, s[10:11]
	v_mov_b32_e32 v140, v193
	v_mov_b32_e32 v141, v193
	v_mov_b32_e32 v142, v193
	v_mov_b32_e32 v143, v193
	v_mov_b32_dpp v140, v131 row_ror:8 row_mask:0xf bank_mask:0xf
	v_mov_b32_dpp v141, v130 row_ror:8 row_mask:0xf bank_mask:0xf
	v_mov_b32_dpp v142, v129 row_ror:8 row_mask:0xf bank_mask:0xf
	v_mov_b32_dpp v143, v128 row_ror:8 row_mask:0xf bank_mask:0xf
	v_cndmask_b32_e64 v128, v140, v201, s[10:11]
	v_cndmask_b32_e64 v129, v141, v244, s[10:11]
	v_cndmask_b32_e64 v130, v142, v245, s[10:11]
	v_cndmask_b32_e64 v131, v143, v246, s[10:11]
	global_store_dwordx4 v[218:219], v[128:131], off
	ds_bpermute_b32 v128, v231, v148
	v_cndmask_b32_e64 v140, v144, v140, s[10:11]
	v_add_co_u32_e32 v130, vcc, 0x4000, v218
	v_cndmask_b32_e64 v141, v145, v141, s[10:11]
	s_waitcnt lgkmcnt(0)
	v_add_f32_e32 v128, v148, v128
	ds_bpermute_b32 v129, v232, v128
	v_cndmask_b32_e64 v142, v146, v142, s[10:11]
	v_cndmask_b32_e64 v143, v147, v143, s[10:11]
	v_addc_co_u32_e32 v131, vcc, 0, v219, vcc
	global_store_dwordx4 v[130:131], v[140:143], off
	s_and_saveexec_b64 s[52:53], s[4:5]
	s_cbranch_execz .LBB0_226
	v_lshlrev_b64 v[130:131], 6, v[208:209]
	v_lshl_add_u64 v[130:131], s[42:43], 0, v[130:131]
	v_lshl_add_u64 v[130:131], s[50:51], 2, v[130:131]
	s_lshl_b32 s36, s72, 2
	v_lshl_add_u64 v[130:131], v[130:131], 0, s[36:37]
	s_waitcnt lgkmcnt(0)
	v_add_f32_e32 v128, v128, v129
	global_store_dword v[130:131], v128, off

.LBB0_246:
	s_waitcnt vmcnt(0)
	v_readlane_b32 s90, v254, 11
	v_readlane_b32 s71, v254, 10
	v_readlane_b32 s91, v254, 12
	s_and_b64 vcc, exec, s[48:49]
	s_cbranch_vccz .Lna_2
	s_barrier

.LBB0_313:
	ds_read_b128 v[128:131], v179
	ds_read_b128 v[132:135], v179 offset:1024
	ds_read_b128 v[136:139], v179 offset:2048
	ds_read_b128 v[140:143], v179 offset:3072
	ds_read_b128 v[188:191], v181
	ds_read_b128 v[192:195], v181 offset:1024
	ds_read_b128 v[196:199], v181 offset:2048
	ds_read_b128 v[200:203], v181 offset:3072
	s_add_u32 s54, s52, 0xfffc0080
	s_addc_u32 s55, s53, -1
	s_cmp_eq_u32 s69, 12
	s_cselect_b32 s57, s10, s55
	s_cselect_b32 s56, s43, s54
	s_cselect_b32 s55, s45, s68
	s_cselect_b32 s54, s51, s67
	v_lshl_add_u64 v[238:239], s[52:53], 0, v[162:163]
	s_add_i32 m0, s75, 0xc000
	ds_read_b128 v[204:207], v183
	ds_read_b128 v[208:211], v183 offset:1024
	ds_read_b128 v[212:215], v183 offset:2048
	ds_read_b128 v[216:219], v183 offset:3072
	ds_read_b128 v[220:223], v183 offset:4096
	ds_read_b128 v[224:227], v183 offset:5120
	ds_read_b128 v[230:233], v183 offset:6144
	ds_read_b128 v[234:237], v183 offset:7168
	global_load_lds_dwordx4 v[238:239], off
	v_lshl_add_u64 v[238:239], s[52:53], 0, v[164:165]
	s_add_i32 m0, s75, 0xe000
	s_nop 0
	global_load_lds_dwordx4 v[238:239], off
	s_waitcnt vmcnt(8)
	s_waitcnt lgkmcnt(0)
	s_setprio 1
	s_barrier
	v_mfma_f32_16x16x32_bf16 v[124:127], v[128:131], v[204:207], v[124:127]
	v_mfma_f32_16x16x32_bf16 v[120:123], v[136:139], v[204:207], v[120:123]
	v_mfma_f32_16x16x32_bf16 v[108:111], v[128:131], v[212:215], v[108:111]
	v_mfma_f32_16x16x32_bf16 v[104:107], v[136:139], v[212:215], v[104:107]
	v_mfma_f32_16x16x32_bf16 v[92:95], v[128:131], v[220:223], v[92:95]
	v_mfma_f32_16x16x32_bf16 v[88:91], v[136:139], v[220:223], v[88:91]
	v_mfma_f32_16x16x32_bf16 v[76:79], v[128:131], v[230:233], v[76:79]
	v_mfma_f32_16x16x32_bf16 v[72:75], v[136:139], v[230:233], v[72:75]
	v_mfma_f32_16x16x32_bf16 v[124:127], v[132:135], v[208:211], v[124:127]
	v_mfma_f32_16x16x32_bf16 v[120:123], v[140:143], v[208:211], v[120:123]
	v_mfma_f32_16x16x32_bf16 v[108:111], v[132:135], v[216:219], v[108:111]
	v_mfma_f32_16x16x32_bf16 v[104:107], v[140:143], v[216:219], v[104:107]
	v_mfma_f32_16x16x32_bf16 v[92:95], v[132:135], v[224:227], v[92:95]
	v_mfma_f32_16x16x32_bf16 v[88:91], v[140:143], v[224:227], v[88:91]
	v_mfma_f32_16x16x32_bf16 v[76:79], v[132:135], v[234:237], v[76:79]
	v_mfma_f32_16x16x32_bf16 v[72:75], v[140:143], v[234:237], v[72:75]
	v_mfma_f32_16x16x32_bf16 v[116:119], v[188:191], v[204:207], v[116:119]
	v_mfma_f32_16x16x32_bf16 v[112:115], v[196:199], v[204:207], v[112:115]
	v_mfma_f32_16x16x32_bf16 v[100:103], v[188:191], v[212:215], v[100:103]
	v_mfma_f32_16x16x32_bf16 v[96:99], v[196:199], v[212:215], v[96:99]
	v_mfma_f32_16x16x32_bf16 v[84:87], v[188:191], v[220:223], v[84:87]
	v_mfma_f32_16x16x32_bf16 v[80:83], v[196:199], v[220:223], v[80:83]
	v_mfma_f32_16x16x32_bf16 v[68:71], v[188:191], v[230:233], v[68:71]
	v_mfma_f32_16x16x32_bf16 v[64:67], v[196:199], v[230:233], v[64:67]
	v_mfma_f32_16x16x32_bf16 v[116:119], v[192:195], v[208:211], v[116:119]
	v_mfma_f32_16x16x32_bf16 v[112:115], v[200:203], v[208:211], v[112:115]
	v_mfma_f32_16x16x32_bf16 v[100:103], v[192:195], v[216:219], v[100:103]
	v_mfma_f32_16x16x32_bf16 v[96:99], v[200:203], v[216:219], v[96:99]
	v_mfma_f32_16x16x32_bf16 v[84:87], v[192:195], v[224:227], v[84:87]
	v_mfma_f32_16x16x32_bf16 v[80:83], v[200:203], v[224:227], v[80:83]
	v_mfma_f32_16x16x32_bf16 v[68:71], v[192:195], v[234:237], v[68:71]
	v_mfma_f32_16x16x32_bf16 v[64:67], v[200:203], v[234:237], v[64:67]
	s_barrier
	s_setprio 0
	s_add_i32 vcc_lo, s92, s72
	v_lshl_add_u64 v[238:239], s[54:55], 0, v[148:149]
	s_mov_b32 m0, vcc_lo
	ds_read_b128 v[204:207], v183 offset:16384
	ds_read_b128 v[208:211], v183 offset:17408
	ds_read_b128 v[212:215], v183 offset:18432
	ds_read_b128 v[216:219], v183 offset:19456
	ds_read_b128 v[220:223], v183 offset:20480
	ds_read_b128 v[224:227], v183 offset:21504
	ds_read_b128 v[230:233], v183 offset:22528
	ds_read_b128 v[234:237], v183 offset:23552
	global_load_lds_dwordx4 v[238:239], off
	s_add_i32 m0, vcc_lo, 0x2000
	s_add_u32 vcc_lo, s54, 0x40000
	v_lshl_add_u64 v[240:241], s[54:55], 0, v[144:145]
	s_addc_u32 vcc_hi, s55, 0
	s_add_i32 s83, s93, s72
	global_load_lds_dwordx4 v[240:241], off
	v_lshl_add_u64 v[242:243], vcc, 0, v[148:149]
	s_mov_b32 m0, s83
	v_lshl_add_u64 v[244:245], s[56:57], 0, v[146:147]
	global_load_lds_dwordx4 v[242:243], off
	v_lshl_add_u64 v[242:243], vcc, 0, v[144:145]
	s_add_i32 m0, s83, 0x2000
	s_nop 0
	global_load_lds_dwordx4 v[242:243], off
	v_lshl_add_u64 v[242:243], s[56:57], 0, v[150:151]
	s_mov_b32 m0, s75
	s_nop 0
	global_load_lds_dwordx4 v[242:243], off
	s_mov_b32 m0, s76
	s_nop 0
	global_load_lds_dwordx4 v[244:245], off
	s_waitcnt vmcnt(8)
	s_waitcnt lgkmcnt(0)
	s_setprio 1
	s_barrier
	v_mfma_f32_16x16x32_bf16 v[60:63], v[128:131], v[204:207], v[60:63]
	v_mfma_f32_16x16x32_bf16 v[56:59], v[136:139], v[204:207], v[56:59]
	v_mfma_f32_16x16x32_bf16 v[44:47], v[128:131], v[212:215], v[44:47]
	v_mfma_f32_16x16x32_bf16 v[40:43], v[136:139], v[212:215], v[40:43]
	v_mfma_f32_16x16x32_bf16 v[28:31], v[128:131], v[220:223], v[28:31]
	v_mfma_f32_16x16x32_bf16 v[24:27], v[136:139], v[220:223], v[24:27]
	v_mfma_f32_16x16x32_bf16 v[12:15], v[128:131], v[230:233], v[12:15]
	v_mfma_f32_16x16x32_bf16 v[8:11], v[136:139], v[230:233], v[8:11]
	v_mfma_f32_16x16x32_bf16 v[60:63], v[132:135], v[208:211], v[60:63]
	v_mfma_f32_16x16x32_bf16 v[56:59], v[140:143], v[208:211], v[56:59]
	v_mfma_f32_16x16x32_bf16 v[44:47], v[132:135], v[216:219], v[44:47]
	v_mfma_f32_16x16x32_bf16 v[40:43], v[140:143], v[216:219], v[40:43]
	v_mfma_f32_16x16x32_bf16 v[28:31], v[132:135], v[224:227], v[28:31]
	v_mfma_f32_16x16x32_bf16 v[24:27], v[140:143], v[224:227], v[24:27]
	v_mfma_f32_16x16x32_bf16 v[12:15], v[132:135], v[234:237], v[12:15]
	v_mfma_f32_16x16x32_bf16 v[8:11], v[140:143], v[234:237], v[8:11]
	v_mfma_f32_16x16x32_bf16 v[52:55], v[188:191], v[204:207], v[52:55]
	v_mfma_f32_16x16x32_bf16 v[48:51], v[196:199], v[204:207], v[48:51]
	v_mfma_f32_16x16x32_bf16 v[36:39], v[188:191], v[212:215], v[36:39]
	v_mfma_f32_16x16x32_bf16 v[32:35], v[196:199], v[212:215], v[32:35]
	v_mfma_f32_16x16x32_bf16 v[20:23], v[188:191], v[220:223], v[20:23]
	v_mfma_f32_16x16x32_bf16 v[16:19], v[196:199], v[220:223], v[16:19]
	v_mfma_f32_16x16x32_bf16 v[4:7], v[188:191], v[230:233], v[4:7]
	v_mfma_f32_16x16x32_bf16 v[0:3], v[196:199], v[230:233], v[0:3]
	v_mfma_f32_16x16x32_bf16 v[52:55], v[192:195], v[208:211], v[52:55]
	v_mfma_f32_16x16x32_bf16 v[48:51], v[200:203], v[208:211], v[48:51]
	v_mfma_f32_16x16x32_bf16 v[36:39], v[192:195], v[216:219], v[36:39]
	v_mfma_f32_16x16x32_bf16 v[32:35], v[200:203], v[216:219], v[32:35]
	v_mfma_f32_16x16x32_bf16 v[20:23], v[192:195], v[224:227], v[20:23]
	v_mfma_f32_16x16x32_bf16 v[16:19], v[200:203], v[224:227], v[16:19]
	v_mfma_f32_16x16x32_bf16 v[4:7], v[192:195], v[234:237], v[4:7]
	v_mfma_f32_16x16x32_bf16 v[0:3], v[200:203], v[234:237], v[0:3]
	s_barrier
	s_setprio 0
	s_add_i32 s83, 0, 0x18000
	s_add_i32 vcc_lo, 0, 0x1c000
	v_add_u32_e32 v140, s83, v157
	v_add_u32_e32 v171, vcc_lo, v157
	ds_read_b128 v[128:131], v140
	ds_read_b128 v[132:135], v140 offset:1024
	ds_read_b128 v[136:139], v140 offset:2048
	ds_read_b128 v[140:143], v140 offset:3072
	ds_read_b128 v[188:191], v171
	ds_read_b128 v[192:195], v171 offset:1024
	ds_read_b128 v[196:199], v171 offset:2048
	ds_read_b128 v[200:203], v171 offset:3072
	s_add_u32 s56, s56, 0x40000
	s_addc_u32 s57, s57, 0
	s_mov_b32 m0, s77
	v_lshl_add_u64 v[246:247], s[56:57], 0, v[150:151]
	ds_read_b128 v[204:207], v183 offset:32768
	ds_read_b128 v[208:211], v183 offset:33792
	ds_read_b128 v[212:215], v183 offset:34816
	ds_read_b128 v[216:219], v183 offset:35840
	ds_read_b128 v[220:223], v183 offset:36864
	ds_read_b128 v[224:227], v183 offset:37888
	ds_read_b128 v[230:233], v183 offset:38912
	ds_read_b128 v[234:237], v183 offset:39936
	global_load_lds_dwordx4 v[246:247], off
	v_lshl_add_u64 v[246:247], s[56:57], 0, v[146:147]
	s_mov_b32 m0, s78
	s_nop 0
	global_load_lds_dwordx4 v[246:247], off
	s_waitcnt vmcnt(8)
	s_waitcnt lgkmcnt(0)
	s_setprio 1
	s_barrier
	v_mfma_f32_16x16x32_bf16 v[124:127], v[128:131], v[204:207], v[124:127]
	v_mfma_f32_16x16x32_bf16 v[120:123], v[136:139], v[204:207], v[120:123]
	v_mfma_f32_16x16x32_bf16 v[108:111], v[128:131], v[212:215], v[108:111]
	v_mfma_f32_16x16x32_bf16 v[104:107], v[136:139], v[212:215], v[104:107]
	v_mfma_f32_16x16x32_bf16 v[92:95], v[128:131], v[220:223], v[92:95]
	v_mfma_f32_16x16x32_bf16 v[88:91], v[136:139], v[220:223], v[88:91]
	v_mfma_f32_16x16x32_bf16 v[76:79], v[128:131], v[230:233], v[76:79]
	v_mfma_f32_16x16x32_bf16 v[72:75], v[136:139], v[230:233], v[72:75]
	v_mfma_f32_16x16x32_bf16 v[124:127], v[132:135], v[208:211], v[124:127]
	v_mfma_f32_16x16x32_bf16 v[120:123], v[140:143], v[208:211], v[120:123]
	v_mfma_f32_16x16x32_bf16 v[108:111], v[132:135], v[216:219], v[108:111]
	v_mfma_f32_16x16x32_bf16 v[104:107], v[140:143], v[216:219], v[104:107]
	v_mfma_f32_16x16x32_bf16 v[92:95], v[132:135], v[224:227], v[92:95]
	v_mfma_f32_16x16x32_bf16 v[88:91], v[140:143], v[224:227], v[88:91]
	v_mfma_f32_16x16x32_bf16 v[76:79], v[132:135], v[234:237], v[76:79]
	v_mfma_f32_16x16x32_bf16 v[72:75], v[140:143], v[234:237], v[72:75]
	v_mfma_f32_16x16x32_bf16 v[116:119], v[188:191], v[204:207], v[116:119]
	v_mfma_f32_16x16x32_bf16 v[112:115], v[196:199], v[204:207], v[112:115]
	v_mfma_f32_16x16x32_bf16 v[100:103], v[188:191], v[212:215], v[100:103]
	v_mfma_f32_16x16x32_bf16 v[96:99], v[196:199], v[212:215], v[96:99]
	v_mfma_f32_16x16x32_bf16 v[84:87], v[188:191], v[220:223], v[84:87]
	v_mfma_f32_16x16x32_bf16 v[80:83], v[196:199], v[220:223], v[80:83]
	v_mfma_f32_16x16x32_bf16 v[68:71], v[188:191], v[230:233], v[68:71]
	v_mfma_f32_16x16x32_bf16 v[64:67], v[196:199], v[230:233], v[64:67]
	v_mfma_f32_16x16x32_bf16 v[116:119], v[192:195], v[208:211], v[116:119]
	v_mfma_f32_16x16x32_bf16 v[112:115], v[200:203], v[208:211], v[112:115]
	v_mfma_f32_16x16x32_bf16 v[100:103], v[192:195], v[216:219], v[100:103]
	v_mfma_f32_16x16x32_bf16 v[96:99], v[200:203], v[216:219], v[96:99]
	v_mfma_f32_16x16x32_bf16 v[84:87], v[192:195], v[224:227], v[84:87]
	v_mfma_f32_16x16x32_bf16 v[80:83], v[200:203], v[224:227], v[80:83]
	v_mfma_f32_16x16x32_bf16 v[68:71], v[192:195], v[234:237], v[68:71]
	v_mfma_f32_16x16x32_bf16 v[64:67], v[200:203], v[234:237], v[64:67]
	s_barrier
	s_setprio 0
	s_add_i32 s56, s83, s72
	v_lshl_add_u64 v[238:239], v[238:239], 0, s[38:39]
	s_mov_b32 m0, s56
	ds_read_b128 v[204:207], v183 offset:49152
	ds_read_b128 v[208:211], v183 offset:50176
	ds_read_b128 v[212:215], v183 offset:51200
	ds_read_b128 v[216:219], v183 offset:52224
	ds_read_b128 v[220:223], v183 offset:53248
	ds_read_b128 v[224:227], v183 offset:54272
	ds_read_b128 v[230:233], v183 offset:55296
	ds_read_b128 v[234:237], v183 offset:56320
	global_load_lds_dwordx4 v[238:239], off
	s_add_i32 m0, s56, 0x2000
	s_add_u32 s54, s54, 0x40080
	v_lshl_add_u64 v[238:239], v[240:241], 0, s[38:39]
	s_addc_u32 s55, s55, 0
	s_add_i32 s56, vcc_lo, s72
	global_load_lds_dwordx4 v[238:239], off
	v_lshl_add_u64 v[238:239], s[54:55], 0, v[148:149]
	s_mov_b32 m0, s56
	s_nop 0
	global_load_lds_dwordx4 v[238:239], off
	v_lshl_add_u64 v[238:239], s[54:55], 0, v[144:145]
	s_add_i32 m0, s56, 0x2000
	s_nop 0
	global_load_lds_dwordx4 v[238:239], off
	v_lshl_add_u64 v[238:239], v[242:243], 0, s[38:39]
	s_mov_b32 m0, s87
	s_nop 0
	global_load_lds_dwordx4 v[238:239], off
	v_lshl_add_u64 v[238:239], v[244:245], 0, s[38:39]
	s_mov_b32 m0, s88
	s_nop 0
	global_load_lds_dwordx4 v[238:239], off
	s_waitcnt vmcnt(8)
	s_waitcnt lgkmcnt(0)
	s_setprio 1
	s_barrier
	v_mfma_f32_16x16x32_bf16 v[60:63], v[128:131], v[204:207], v[60:63]
	v_mfma_f32_16x16x32_bf16 v[56:59], v[136:139], v[204:207], v[56:59]
	v_mfma_f32_16x16x32_bf16 v[44:47], v[128:131], v[212:215], v[44:47]
	v_mfma_f32_16x16x32_bf16 v[40:43], v[136:139], v[212:215], v[40:43]
	v_mfma_f32_16x16x32_bf16 v[28:31], v[128:131], v[220:223], v[28:31]
	v_mfma_f32_16x16x32_bf16 v[24:27], v[136:139], v[220:223], v[24:27]
	v_mfma_f32_16x16x32_bf16 v[12:15], v[128:131], v[230:233], v[12:15]
	v_mfma_f32_16x16x32_bf16 v[8:11], v[136:139], v[230:233], v[8:11]
	v_mfma_f32_16x16x32_bf16 v[60:63], v[132:135], v[208:211], v[60:63]
	v_mfma_f32_16x16x32_bf16 v[56:59], v[140:143], v[208:211], v[56:59]
	v_mfma_f32_16x16x32_bf16 v[44:47], v[132:135], v[216:219], v[44:47]
	v_mfma_f32_16x16x32_bf16 v[40:43], v[140:143], v[216:219], v[40:43]
	v_mfma_f32_16x16x32_bf16 v[28:31], v[132:135], v[224:227], v[28:31]
	v_mfma_f32_16x16x32_bf16 v[24:27], v[140:143], v[224:227], v[24:27]
	v_mfma_f32_16x16x32_bf16 v[12:15], v[132:135], v[234:237], v[12:15]
	v_mfma_f32_16x16x32_bf16 v[8:11], v[140:143], v[234:237], v[8:11]
	v_mfma_f32_16x16x32_bf16 v[52:55], v[188:191], v[204:207], v[52:55]
	v_mfma_f32_16x16x32_bf16 v[48:51], v[196:199], v[204:207], v[48:51]
	v_mfma_f32_16x16x32_bf16 v[36:39], v[188:191], v[212:215], v[36:39]
	v_mfma_f32_16x16x32_bf16 v[32:35], v[196:199], v[212:215], v[32:35]
	v_mfma_f32_16x16x32_bf16 v[20:23], v[188:191], v[220:223], v[20:23]
	v_mfma_f32_16x16x32_bf16 v[16:19], v[196:199], v[220:223], v[16:19]
	v_mfma_f32_16x16x32_bf16 v[4:7], v[188:191], v[230:233], v[4:7]
	v_mfma_f32_16x16x32_bf16 v[0:3], v[196:199], v[230:233], v[0:3]
	v_mfma_f32_16x16x32_bf16 v[52:55], v[192:195], v[208:211], v[52:55]
	v_mfma_f32_16x16x32_bf16 v[48:51], v[200:203], v[208:211], v[48:51]
	v_mfma_f32_16x16x32_bf16 v[36:39], v[192:195], v[216:219], v[36:39]
	v_mfma_f32_16x16x32_bf16 v[32:35], v[200:203], v[216:219], v[32:35]
	v_mfma_f32_16x16x32_bf16 v[20:23], v[192:195], v[224:227], v[20:23]
	v_mfma_f32_16x16x32_bf16 v[16:19], v[200:203], v[224:227], v[16:19]
	v_mfma_f32_16x16x32_bf16 v[4:7], v[192:195], v[234:237], v[4:7]
	v_mfma_f32_16x16x32_bf16 v[0:3], v[200:203], v[234:237], v[0:3]
	s_barrier
	s_setprio 0
	s_add_i32 s69, s69, 2
	s_add_u32 s52, s52, 0x100
	s_addc_u32 s53, s53, 0
	s_add_u32 s67, s67, 0x100
	s_addc_u32 s68, s68, 0
	s_cmp_gt_u32 s69, 13
	s_cbranch_scc0 .LBB0_313
	s_and_b64 vcc, exec, s[40:41]
	s_cbranch_vccz .LBB0_316
.LBB0_316:
	s_mul_i32 s98, s50, 0x667
	s_lshr_b32 s98, s98, 16
	s_mul_i32 s98, s98, 40
	s_sub_u32 s98, s50, s98
	s_lshr_b32 s98, s98, 3
	s_lshl_b32 s98, s98, 10
	s_add_u32 s98, s98, 0x20800
	v_add_u32_e32 v139, s81, v155
	v_lshl_add_u32 v139, v139, 2, s98
	ds_read_b32 v128, v139 offset:0
	ds_read_b32 v129, v139 offset:64
	ds_read_b32 v130, v139 offset:192
	ds_read_b32 v131, v139 offset:512
	ds_read_b32 v132, v139 offset:640
	ds_read_b32 v133, v139 offset:128
	ds_read_b32 v134, v139 offset:576
	ds_read_b32 v135, v139 offset:704
	s_waitcnt lgkmcnt(0)
	s_lshl_b32 s10, s50, 8
	s_add_i32 s52, s10, s81
	v_or_b32_e32 v136, s52, v155
	v_or_b32_e32 v188, 16, v136
	v_or_b32_e32 v142, 32, v136
	v_or_b32_e32 v140, 48, v136
	v_ashrrev_i32_e32 v137, 31, v136
	s_nop 0
	s_nop 0
	s_nop 0
	v_add_u32_e32 v138, 0x80, v136
	s_nop 0
	s_cmp_gt_i32 s66, 3
	s_mov_b64 s[54:55], -1
	s_waitcnt lgkmcnt(4)
	s_waitcnt lgkmcnt(4)
	s_waitcnt lgkmcnt(3)
	s_waitcnt lgkmcnt(2)
	s_waitcnt lgkmcnt(3)
	s_waitcnt lgkmcnt(7)
	s_waitcnt lgkmcnt(6)
	s_waitcnt lgkmcnt(5)
	s_waitcnt lgkmcnt(4)
	s_waitcnt lgkmcnt(3)
	v_mov_b32_e32 v186, v128
	s_waitcnt lgkmcnt(2)
	v_mov_b32_e32 v184, v129
	s_waitcnt lgkmcnt(2)
	v_mov_b32_e32 v180, v130
	s_waitcnt lgkmcnt(1)
	v_mov_b32_e32 v178, v131
	s_waitcnt lgkmcnt(2)
	s_waitcnt lgkmcnt(1)
	v_mov_b32_e32 v174, v132
	s_waitcnt lgkmcnt(0)
	v_mov_b32_e32 v182, v133
	v_mov_b32_e32 v176, v134
	v_mov_b32_e32 v172, v135
	s_cbranch_scc1 .LBB0_319
	s_andn2_b64 vcc, exec, s[54:55]
	s_cbranch_vccz .LBB0_328

.LBB0_331:
	s_waitcnt vmcnt(0)
	v_readlane_b32 s90, v254, 11
	v_readlane_b32 s71, v254, 10
	v_readlane_b32 s91, v254, 12
	s_and_b64 vcc, exec, s[40:41]
	s_cbranch_vccz .Lna_3
	s_barrier

.LBB0_668:
	ds_read_b128 v[80:83], v216
	ds_read_b128 v[84:87], v216 offset:1024
	ds_read_b128 v[104:107], v216 offset:2048
	ds_read_b128 v[108:111], v216 offset:3072
	ds_read_b128 v[128:131], v217
	ds_read_b128 v[132:135], v217 offset:1024
	ds_read_b128 v[152:155], v217 offset:2048
	ds_read_b128 v[156:159], v217 offset:3072
	s_add_u32 s46, s44, 0xfffc0080
	s_addc_u32 s47, s45, -1
	s_cmp_eq_u32 s95, 12
	s_cselect_b32 s49, s23, s47
	s_cselect_b32 s48, s43, s46
	s_cselect_b32 s47, s37, s94
	s_cselect_b32 s46, s92, s93
	v_lshl_add_u64 v[224:225], s[44:45], 0, v[194:195]
	s_add_i32 m0, s53, 0xc000
	ds_read_b128 v[160:163], v218
	ds_read_b128 v[164:167], v218 offset:1024
	ds_read_b128 v[168:171], v218 offset:2048
	ds_read_b128 v[172:175], v218 offset:3072
	ds_read_b128 v[176:179], v218 offset:4096
	ds_read_b128 v[180:183], v218 offset:5120
	ds_read_b128 v[208:211], v218 offset:6144
	ds_read_b128 v[220:223], v218 offset:7168
	global_load_lds_dwordx4 v[224:225], off
	v_lshl_add_u64 v[224:225], s[44:45], 0, v[196:197]
	s_add_i32 m0, s53, 0xe000
	s_nop 0
	global_load_lds_dwordx4 v[224:225], off
	s_waitcnt vmcnt(8)
	s_waitcnt lgkmcnt(0)
	s_setprio 1
	s_barrier
	v_mfma_f32_16x16x32_bf16 v[148:151], v[80:83], v[160:163], v[148:151]
	v_mfma_f32_16x16x32_bf16 v[144:147], v[104:107], v[160:163], v[144:147]
	v_mfma_f32_16x16x32_bf16 v[124:127], v[80:83], v[168:171], v[124:127]
	v_mfma_f32_16x16x32_bf16 v[120:123], v[104:107], v[168:171], v[120:123]
	v_mfma_f32_16x16x32_bf16 v[100:103], v[80:83], v[176:179], v[100:103]
	v_mfma_f32_16x16x32_bf16 v[96:99], v[104:107], v[176:179], v[96:99]
	v_mfma_f32_16x16x32_bf16 v[76:79], v[80:83], v[208:211], v[76:79]
	v_mfma_f32_16x16x32_bf16 v[72:75], v[104:107], v[208:211], v[72:75]
	v_mfma_f32_16x16x32_bf16 v[148:151], v[84:87], v[164:167], v[148:151]
	v_mfma_f32_16x16x32_bf16 v[144:147], v[108:111], v[164:167], v[144:147]
	v_mfma_f32_16x16x32_bf16 v[124:127], v[84:87], v[172:175], v[124:127]
	v_mfma_f32_16x16x32_bf16 v[120:123], v[108:111], v[172:175], v[120:123]
	v_mfma_f32_16x16x32_bf16 v[100:103], v[84:87], v[180:183], v[100:103]
	v_mfma_f32_16x16x32_bf16 v[96:99], v[108:111], v[180:183], v[96:99]
	v_mfma_f32_16x16x32_bf16 v[76:79], v[84:87], v[220:223], v[76:79]
	v_mfma_f32_16x16x32_bf16 v[72:75], v[108:111], v[220:223], v[72:75]
	v_mfma_f32_16x16x32_bf16 v[140:143], v[128:131], v[160:163], v[140:143]
	v_mfma_f32_16x16x32_bf16 v[136:139], v[152:155], v[160:163], v[136:139]
	v_mfma_f32_16x16x32_bf16 v[116:119], v[128:131], v[168:171], v[116:119]
	v_mfma_f32_16x16x32_bf16 v[112:115], v[152:155], v[168:171], v[112:115]
	v_mfma_f32_16x16x32_bf16 v[92:95], v[128:131], v[176:179], v[92:95]
	v_mfma_f32_16x16x32_bf16 v[88:91], v[152:155], v[176:179], v[88:91]
	v_mfma_f32_16x16x32_bf16 v[68:71], v[128:131], v[208:211], v[68:71]
	v_mfma_f32_16x16x32_bf16 v[64:67], v[152:155], v[208:211], v[64:67]
	v_mfma_f32_16x16x32_bf16 v[140:143], v[132:135], v[164:167], v[140:143]
	v_mfma_f32_16x16x32_bf16 v[136:139], v[156:159], v[164:167], v[136:139]
	v_mfma_f32_16x16x32_bf16 v[116:119], v[132:135], v[172:175], v[116:119]
	v_mfma_f32_16x16x32_bf16 v[112:115], v[156:159], v[172:175], v[112:115]
	v_mfma_f32_16x16x32_bf16 v[92:95], v[132:135], v[180:183], v[92:95]
	v_mfma_f32_16x16x32_bf16 v[88:91], v[156:159], v[180:183], v[88:91]
	v_mfma_f32_16x16x32_bf16 v[68:71], v[132:135], v[220:223], v[68:71]
	v_mfma_f32_16x16x32_bf16 v[64:67], v[156:159], v[220:223], v[64:67]
	s_barrier
	s_setprio 0
	s_add_i32 s83, s78, s52
	v_lshl_add_u64 v[224:225], s[46:47], 0, v[186:187]
	s_mov_b32 m0, s83
	ds_read_b128 v[160:163], v218 offset:16384
	ds_read_b128 v[164:167], v218 offset:17408
	ds_read_b128 v[168:171], v218 offset:18432
	ds_read_b128 v[172:175], v218 offset:19456
	ds_read_b128 v[176:179], v218 offset:20480
	ds_read_b128 v[180:183], v218 offset:21504
	ds_read_b128 v[208:211], v218 offset:22528
	ds_read_b128 v[220:223], v218 offset:23552
	global_load_lds_dwordx4 v[224:225], off
	s_add_i32 m0, s83, 0x2000
	s_add_u32 s96, s46, 0x40000
	v_lshl_add_u64 v[226:227], s[46:47], 0, v[190:191]
	s_addc_u32 s97, s47, 0
	s_add_i32 s83, s79, s52
	global_load_lds_dwordx4 v[226:227], off
	v_lshl_add_u64 v[230:231], s[96:97], 0, v[186:187]
	s_mov_b32 m0, s83
	v_lshl_add_u64 v[232:233], s[48:49], 0, v[188:189]
	global_load_lds_dwordx4 v[230:231], off
	v_lshl_add_u64 v[230:231], s[96:97], 0, v[190:191]
	s_add_i32 m0, s83, 0x2000
	s_nop 0
	global_load_lds_dwordx4 v[230:231], off
	v_lshl_add_u64 v[230:231], s[48:49], 0, v[184:185]
	s_mov_b32 m0, s53
	s_nop 0
	global_load_lds_dwordx4 v[230:231], off
	s_mov_b32 m0, s54
	s_nop 0
	global_load_lds_dwordx4 v[232:233], off
	s_waitcnt vmcnt(8)
	s_waitcnt lgkmcnt(0)
	s_setprio 1
	s_barrier
	v_mfma_f32_16x16x32_bf16 v[60:63], v[80:83], v[160:163], v[60:63]
	v_mfma_f32_16x16x32_bf16 v[56:59], v[104:107], v[160:163], v[56:59]
	v_mfma_f32_16x16x32_bf16 v[44:47], v[80:83], v[168:171], v[44:47]
	v_mfma_f32_16x16x32_bf16 v[40:43], v[104:107], v[168:171], v[40:43]
	v_mfma_f32_16x16x32_bf16 v[28:31], v[80:83], v[176:179], v[28:31]
	v_mfma_f32_16x16x32_bf16 v[24:27], v[104:107], v[176:179], v[24:27]
	v_mfma_f32_16x16x32_bf16 v[12:15], v[80:83], v[208:211], v[12:15]
	v_mfma_f32_16x16x32_bf16 v[8:11], v[104:107], v[208:211], v[8:11]
	v_mfma_f32_16x16x32_bf16 v[60:63], v[84:87], v[164:167], v[60:63]
	v_mfma_f32_16x16x32_bf16 v[56:59], v[108:111], v[164:167], v[56:59]
	v_mfma_f32_16x16x32_bf16 v[44:47], v[84:87], v[172:175], v[44:47]
	v_mfma_f32_16x16x32_bf16 v[40:43], v[108:111], v[172:175], v[40:43]
	v_mfma_f32_16x16x32_bf16 v[28:31], v[84:87], v[180:183], v[28:31]
	v_mfma_f32_16x16x32_bf16 v[24:27], v[108:111], v[180:183], v[24:27]
	v_mfma_f32_16x16x32_bf16 v[12:15], v[84:87], v[220:223], v[12:15]
	v_mfma_f32_16x16x32_bf16 v[8:11], v[108:111], v[220:223], v[8:11]
	v_mfma_f32_16x16x32_bf16 v[52:55], v[128:131], v[160:163], v[52:55]
	v_mfma_f32_16x16x32_bf16 v[48:51], v[152:155], v[160:163], v[48:51]
	v_mfma_f32_16x16x32_bf16 v[36:39], v[128:131], v[168:171], v[36:39]
	v_mfma_f32_16x16x32_bf16 v[32:35], v[152:155], v[168:171], v[32:35]
	v_mfma_f32_16x16x32_bf16 v[20:23], v[128:131], v[176:179], v[20:23]
	v_mfma_f32_16x16x32_bf16 v[16:19], v[152:155], v[176:179], v[16:19]
	v_mfma_f32_16x16x32_bf16 v[4:7], v[128:131], v[208:211], v[4:7]
	v_mfma_f32_16x16x32_bf16 v[0:3], v[152:155], v[208:211], v[0:3]
	v_mfma_f32_16x16x32_bf16 v[52:55], v[132:135], v[164:167], v[52:55]
	v_mfma_f32_16x16x32_bf16 v[48:51], v[156:159], v[164:167], v[48:51]
	v_mfma_f32_16x16x32_bf16 v[36:39], v[132:135], v[172:175], v[36:39]
	v_mfma_f32_16x16x32_bf16 v[32:35], v[156:159], v[172:175], v[32:35]
	v_mfma_f32_16x16x32_bf16 v[20:23], v[132:135], v[180:183], v[20:23]
	v_mfma_f32_16x16x32_bf16 v[16:19], v[156:159], v[180:183], v[16:19]
	v_mfma_f32_16x16x32_bf16 v[4:7], v[132:135], v[220:223], v[4:7]
	v_mfma_f32_16x16x32_bf16 v[0:3], v[156:159], v[220:223], v[0:3]
	s_barrier
	s_setprio 0
	s_add_i32 s83, 0, 0x18000
	s_add_i32 s96, 0, 0x1c000
	v_add_u32_e32 v108, s83, v213
	v_add_u32_e32 v156, s96, v213
	ds_read_b128 v[80:83], v108
	ds_read_b128 v[84:87], v108 offset:1024
	ds_read_b128 v[104:107], v108 offset:2048
	ds_read_b128 v[108:111], v108 offset:3072
	ds_read_b128 v[128:131], v156
	ds_read_b128 v[132:135], v156 offset:1024
	ds_read_b128 v[152:155], v156 offset:2048
	ds_read_b128 v[156:159], v156 offset:3072
	s_add_u32 s48, s48, 0x40000
	s_addc_u32 s49, s49, 0
	s_mov_b32 m0, s55
	v_lshl_add_u64 v[234:235], s[48:49], 0, v[184:185]
	ds_read_b128 v[160:163], v218 offset:32768
	ds_read_b128 v[164:167], v218 offset:33792
	ds_read_b128 v[168:171], v218 offset:34816
	ds_read_b128 v[172:175], v218 offset:35840
	ds_read_b128 v[176:179], v218 offset:36864
	ds_read_b128 v[180:183], v218 offset:37888
	ds_read_b128 v[208:211], v218 offset:38912
	ds_read_b128 v[220:223], v218 offset:39936
	global_load_lds_dwordx4 v[234:235], off
	v_lshl_add_u64 v[234:235], s[48:49], 0, v[188:189]
	s_mov_b32 m0, s56
	s_nop 0
	global_load_lds_dwordx4 v[234:235], off
	s_waitcnt vmcnt(8)
	s_waitcnt lgkmcnt(0)
	s_setprio 1
	s_barrier
	v_mfma_f32_16x16x32_bf16 v[148:151], v[80:83], v[160:163], v[148:151]
	v_mfma_f32_16x16x32_bf16 v[144:147], v[104:107], v[160:163], v[144:147]
	v_mfma_f32_16x16x32_bf16 v[124:127], v[80:83], v[168:171], v[124:127]
	v_mfma_f32_16x16x32_bf16 v[120:123], v[104:107], v[168:171], v[120:123]
	v_mfma_f32_16x16x32_bf16 v[100:103], v[80:83], v[176:179], v[100:103]
	v_mfma_f32_16x16x32_bf16 v[96:99], v[104:107], v[176:179], v[96:99]
	v_mfma_f32_16x16x32_bf16 v[76:79], v[80:83], v[208:211], v[76:79]
	v_mfma_f32_16x16x32_bf16 v[72:75], v[104:107], v[208:211], v[72:75]
	v_mfma_f32_16x16x32_bf16 v[148:151], v[84:87], v[164:167], v[148:151]
	v_mfma_f32_16x16x32_bf16 v[144:147], v[108:111], v[164:167], v[144:147]
	v_mfma_f32_16x16x32_bf16 v[124:127], v[84:87], v[172:175], v[124:127]
	v_mfma_f32_16x16x32_bf16 v[120:123], v[108:111], v[172:175], v[120:123]
	v_mfma_f32_16x16x32_bf16 v[100:103], v[84:87], v[180:183], v[100:103]
	v_mfma_f32_16x16x32_bf16 v[96:99], v[108:111], v[180:183], v[96:99]
	v_mfma_f32_16x16x32_bf16 v[76:79], v[84:87], v[220:223], v[76:79]
	v_mfma_f32_16x16x32_bf16 v[72:75], v[108:111], v[220:223], v[72:75]
	v_mfma_f32_16x16x32_bf16 v[140:143], v[128:131], v[160:163], v[140:143]
	v_mfma_f32_16x16x32_bf16 v[136:139], v[152:155], v[160:163], v[136:139]
	v_mfma_f32_16x16x32_bf16 v[116:119], v[128:131], v[168:171], v[116:119]
	v_mfma_f32_16x16x32_bf16 v[112:115], v[152:155], v[168:171], v[112:115]
	v_mfma_f32_16x16x32_bf16 v[92:95], v[128:131], v[176:179], v[92:95]
	v_mfma_f32_16x16x32_bf16 v[88:91], v[152:155], v[176:179], v[88:91]
	v_mfma_f32_16x16x32_bf16 v[68:71], v[128:131], v[208:211], v[68:71]
	v_mfma_f32_16x16x32_bf16 v[64:67], v[152:155], v[208:211], v[64:67]
	v_mfma_f32_16x16x32_bf16 v[140:143], v[132:135], v[164:167], v[140:143]
	v_mfma_f32_16x16x32_bf16 v[136:139], v[156:159], v[164:167], v[136:139]
	v_mfma_f32_16x16x32_bf16 v[116:119], v[132:135], v[172:175], v[116:119]
	v_mfma_f32_16x16x32_bf16 v[112:115], v[156:159], v[172:175], v[112:115]
	v_mfma_f32_16x16x32_bf16 v[92:95], v[132:135], v[180:183], v[92:95]
	v_mfma_f32_16x16x32_bf16 v[88:91], v[156:159], v[180:183], v[88:91]
	v_mfma_f32_16x16x32_bf16 v[68:71], v[132:135], v[220:223], v[68:71]
	v_mfma_f32_16x16x32_bf16 v[64:67], v[156:159], v[220:223], v[64:67]
	s_barrier
	s_setprio 0
	s_add_i32 s48, s83, s52
	v_lshl_add_u64 v[224:225], v[224:225], 0, s[18:19]
	s_mov_b32 m0, s48
	ds_read_b128 v[160:163], v218 offset:49152
	ds_read_b128 v[164:167], v218 offset:50176
	ds_read_b128 v[168:171], v218 offset:51200
	ds_read_b128 v[172:175], v218 offset:52224
	ds_read_b128 v[176:179], v218 offset:53248
	ds_read_b128 v[180:183], v218 offset:54272
	ds_read_b128 v[208:211], v218 offset:55296
	ds_read_b128 v[220:223], v218 offset:56320
	global_load_lds_dwordx4 v[224:225], off
	s_add_i32 m0, s48, 0x2000
	s_add_u32 s46, s46, 0x40080
	v_lshl_add_u64 v[224:225], v[226:227], 0, s[18:19]
	s_addc_u32 s47, s47, 0
	s_add_i32 s48, s96, s52
	global_load_lds_dwordx4 v[224:225], off
	v_lshl_add_u64 v[224:225], s[46:47], 0, v[186:187]
	s_mov_b32 m0, s48
	s_nop 0
	global_load_lds_dwordx4 v[224:225], off
	v_lshl_add_u64 v[224:225], s[46:47], 0, v[190:191]
	s_add_i32 m0, s48, 0x2000
	s_nop 0
	global_load_lds_dwordx4 v[224:225], off
	v_lshl_add_u64 v[224:225], v[230:231], 0, s[18:19]
	s_mov_b32 m0, s68
	s_nop 0
	global_load_lds_dwordx4 v[224:225], off
	v_lshl_add_u64 v[224:225], v[232:233], 0, s[18:19]
	s_mov_b32 m0, s69
	s_nop 0
	global_load_lds_dwordx4 v[224:225], off
	s_waitcnt vmcnt(8)
	s_waitcnt lgkmcnt(0)
	s_setprio 1
	s_barrier
	v_mfma_f32_16x16x32_bf16 v[60:63], v[80:83], v[160:163], v[60:63]
	v_mfma_f32_16x16x32_bf16 v[56:59], v[104:107], v[160:163], v[56:59]
	v_mfma_f32_16x16x32_bf16 v[44:47], v[80:83], v[168:171], v[44:47]
	v_mfma_f32_16x16x32_bf16 v[40:43], v[104:107], v[168:171], v[40:43]
	v_mfma_f32_16x16x32_bf16 v[28:31], v[80:83], v[176:179], v[28:31]
	v_mfma_f32_16x16x32_bf16 v[24:27], v[104:107], v[176:179], v[24:27]
	v_mfma_f32_16x16x32_bf16 v[12:15], v[80:83], v[208:211], v[12:15]
	v_mfma_f32_16x16x32_bf16 v[8:11], v[104:107], v[208:211], v[8:11]
	v_mfma_f32_16x16x32_bf16 v[60:63], v[84:87], v[164:167], v[60:63]
	v_mfma_f32_16x16x32_bf16 v[56:59], v[108:111], v[164:167], v[56:59]
	v_mfma_f32_16x16x32_bf16 v[44:47], v[84:87], v[172:175], v[44:47]
	v_mfma_f32_16x16x32_bf16 v[40:43], v[108:111], v[172:175], v[40:43]
	v_mfma_f32_16x16x32_bf16 v[28:31], v[84:87], v[180:183], v[28:31]
	v_mfma_f32_16x16x32_bf16 v[24:27], v[108:111], v[180:183], v[24:27]
	v_mfma_f32_16x16x32_bf16 v[12:15], v[84:87], v[220:223], v[12:15]
	v_mfma_f32_16x16x32_bf16 v[8:11], v[108:111], v[220:223], v[8:11]
	v_mfma_f32_16x16x32_bf16 v[52:55], v[128:131], v[160:163], v[52:55]
	v_mfma_f32_16x16x32_bf16 v[48:51], v[152:155], v[160:163], v[48:51]
	v_mfma_f32_16x16x32_bf16 v[36:39], v[128:131], v[168:171], v[36:39]
	v_mfma_f32_16x16x32_bf16 v[32:35], v[152:155], v[168:171], v[32:35]
	v_mfma_f32_16x16x32_bf16 v[20:23], v[128:131], v[176:179], v[20:23]
	v_mfma_f32_16x16x32_bf16 v[16:19], v[152:155], v[176:179], v[16:19]
	v_mfma_f32_16x16x32_bf16 v[4:7], v[128:131], v[208:211], v[4:7]
	v_mfma_f32_16x16x32_bf16 v[0:3], v[152:155], v[208:211], v[0:3]
	v_mfma_f32_16x16x32_bf16 v[52:55], v[132:135], v[164:167], v[52:55]
	v_mfma_f32_16x16x32_bf16 v[48:51], v[156:159], v[164:167], v[48:51]
	v_mfma_f32_16x16x32_bf16 v[36:39], v[132:135], v[172:175], v[36:39]
	v_mfma_f32_16x16x32_bf16 v[32:35], v[156:159], v[172:175], v[32:35]
	v_mfma_f32_16x16x32_bf16 v[20:23], v[132:135], v[180:183], v[20:23]
	v_mfma_f32_16x16x32_bf16 v[16:19], v[156:159], v[180:183], v[16:19]
	v_mfma_f32_16x16x32_bf16 v[4:7], v[132:135], v[220:223], v[4:7]
	v_mfma_f32_16x16x32_bf16 v[0:3], v[156:159], v[220:223], v[0:3]
	s_barrier
	s_setprio 0
	s_add_i32 s95, s95, 2
	s_add_u32 s44, s44, 0x100
	s_addc_u32 s45, s45, 0
	s_add_u32 s93, s93, 0x100
	s_addc_u32 s94, s94, 0
	s_cmp_gt_u32 s95, 13
	s_cbranch_scc0 .LBB0_668
	s_and_b64 vcc, exec, s[20:21]
	s_cbranch_vccz .LBB0_671
.LBB0_671:
	s_lshl_b32 s23, s42, 8
	s_add_i32 s42, s23, s67
	s_lshl_b32 s23, s14, 8
	s_ashr_i32 s43, s42, 31
	s_or_b32 s44, s23, s73
	s_lshl_b64 s[46:47], s[42:43], 11
	s_add_u32 s23, s62, s46
	s_addc_u32 s37, s63, s47
	s_ashr_i32 s45, s44, 31
	s_lshl_b64 s[44:45], s[44:45], 1
	s_add_u32 s44, s23, s44
	s_addc_u32 s45, s37, s45
	v_lshl_add_u64 v[208:209], s[44:45], 0, v[192:193]
	v_mov_b32_e32 v203, v193
	v_lshl_add_u64 v[80:81], v[208:209], 0, v[202:203]
	v_mov_b32_e32 v205, v193
	v_lshl_add_u64 v[80:81], v[80:81], 0, v[204:205]
	v_add_co_u32_e32 v82, vcc, s59, v80
	v_mov_b32_e32 v207, v193
	s_nop 0
	v_addc_co_u32_e32 v83, vcc, 0, v81, vcc
	global_load_dwordx4 v[220:223], v[80:81], off
	global_load_dwordx4 v[224:227], v[82:83], off
	v_add_co_u32_e32 v82, vcc, s71, v80
	v_lshl_add_u64 v[208:209], v[208:209], 0, v[206:207]
	s_nop 0
	v_addc_co_u32_e32 v83, vcc, 0, v81, vcc
	v_add_co_u32_e32 v84, vcc, s80, v80
	v_lshl_add_u64 v[210:211], v[208:209], 0, v[204:205]
	s_nop 0
	v_addc_co_u32_e32 v85, vcc, 0, v81, vcc
	global_load_dwordx4 v[180:183], v[82:83], off
	global_load_dwordx4 v[176:179], v[84:85], off
	v_add_co_u32_e32 v82, vcc, s57, v80
	v_mov_b32_e32 v219, v193
	s_nop 0
	v_addc_co_u32_e32 v83, vcc, 0, v81, vcc
	v_add_co_u32_e32 v84, vcc, s58, v80
	v_or_b32_e32 v208, s42, v212
	s_nop 0
	v_addc_co_u32_e32 v85, vcc, 0, v81, vcc
	global_load_dwordx4 v[172:175], v[82:83], off
	global_load_dwordx4 v[168:171], v[84:85], off
	v_add_co_u32_e32 v82, vcc, s70, v80
	s_lshl_b32 s42, s14, 2
	s_nop 0
	v_addc_co_u32_e32 v83, vcc, 0, v81, vcc
	v_add_co_u32_e32 v84, vcc, s72, v80
	s_ashr_i32 s43, s42, 31
	s_nop 0
	v_addc_co_u32_e32 v85, vcc, 0, v81, vcc
	global_load_dwordx4 v[164:167], v[82:83], off
	global_load_dwordx4 v[160:163], v[84:85], off
	v_add_co_u32_e32 v82, vcc, s81, v80
	s_waitcnt vmcnt(0)
	v_cndmask_b32_e64 v209, v220, v224, s[8:9]
	v_addc_co_u32_e32 v83, vcc, 0, v81, vcc
	v_add_co_u32_e32 v84, vcc, s82, v80
	v_cndmask_b32_e64 v207, v221, v225, s[8:9]
	s_nop 0
	v_addc_co_u32_e32 v85, vcc, 0, v81, vcc
	global_load_dwordx4 v[156:159], v[82:83], off
	global_load_dwordx4 v[152:155], v[84:85], off
	v_add_co_u32_e32 v82, vcc, s85, v80
	v_mov_b32_dpp v219, v209 row_ror:8 row_mask:0xf bank_mask:0xf
	s_nop 0
	v_addc_co_u32_e32 v83, vcc, 0, v81, vcc
	v_add_co_u32_e32 v84, vcc, s86, v80
	v_mov_b32_e32 v209, v193
	s_nop 0
	v_addc_co_u32_e32 v85, vcc, 0, v81, vcc
	global_load_dwordx4 v[132:135], v[82:83], off
	global_load_dwordx4 v[128:131], v[84:85], off
	v_add_co_u32_e32 v82, vcc, s87, v80
	v_cndmask_b32_e64 v205, v222, v226, s[8:9]
	s_nop 0
	v_addc_co_u32_e32 v83, vcc, 0, v81, vcc
	v_add_co_u32_e32 v84, vcc, s88, v80
	v_mov_b32_dpp v209, v207 row_ror:8 row_mask:0xf bank_mask:0xf
	s_nop 0
	v_addc_co_u32_e32 v85, vcc, 0, v81, vcc
	global_load_dwordx4 v[108:111], v[82:83], off
	global_load_dwordx4 v[104:107], v[84:85], off
	v_add_co_u32_e32 v82, vcc, s89, v80
	v_mov_b32_e32 v207, v193
	s_nop 0
	v_addc_co_u32_e32 v83, vcc, 0, v81, vcc
	v_add_co_u32_e32 v80, vcc, s90, v80
	v_cndmask_b32_e64 v203, v223, v227, s[8:9]
	s_nop 0
	v_addc_co_u32_e32 v81, vcc, 0, v81, vcc
	global_load_dwordx4 v[84:87], v[82:83], off
	s_nop 0
	global_load_dwordx4 v[80:83], v[80:81], off
	v_mov_b32_dpp v207, v205 row_ror:8 row_mask:0xf bank_mask:0xf
	v_mov_b32_e32 v205, v193
	v_cndmask_b32_e64 v229, v207, v222, s[8:9]
	v_cndmask_b32_e64 v207, v226, v207, s[8:9]
	v_mov_b32_dpp v205, v203 row_ror:8 row_mask:0xf bank_mask:0xf
	v_cndmask_b32_e64 v203, v205, v223, s[8:9]
	v_cndmask_b32_e64 v223, v209, v221, s[8:9]
	v_cndmask_b32_e64 v221, v219, v220, s[8:9]
	v_lshlrev_b32_e32 v220, 16, v221
	v_and_b32_e32 v221, 0xffff0000, v221
	v_lshlrev_b32_e32 v222, 16, v223
	v_and_b32_e32 v223, 0xffff0000, v223
	v_pk_add_f32 v[148:149], v[148:149], v[220:221]
	v_cndmask_b32_e64 v205, v227, v205, s[8:9]
	v_cndmask_b32_e64 v209, v225, v209, s[8:9]
	v_cndmask_b32_e64 v219, v224, v219, s[8:9]
	v_lshlrev_b32_e32 v224, 16, v229
	v_and_b32_e32 v225, 0xffff0000, v229
	v_lshlrev_b32_e32 v226, 16, v203
	v_and_b32_e32 v227, 0xffff0000, v203
	v_pk_add_f32 v[150:151], v[150:151], v[222:223]
	v_cvt_pk_bf16_f32 v203, v148, v149
	v_mul_f32_e32 v149, v149, v149
	v_pk_add_f32 v[144:145], v[144:145], v[224:225]
	v_fmac_f32_e32 v149, v148, v148
	v_mul_f32_e32 v148, v151, v151
	v_cvt_pk_bf16_f32 v220, v150, v151
	v_cvt_pk_bf16_f32 v221, v144, v145
	v_fmac_f32_e32 v148, v150, v150
	v_mul_f32_e32 v145, v145, v145
	v_pk_add_f32 v[146:147], v[146:147], v[226:227]
	v_add_f32_e32 v148, v149, v148
	v_fmac_f32_e32 v145, v144, v144
	v_add_f32_e32 v144, v145, v148
	v_mul_f32_e32 v145, v147, v147
	v_fmac_f32_e32 v145, v146, v146
	v_add_f32_e32 v223, v145, v144
	v_lshlrev_b32_e32 v144, 16, v219
	v_and_b32_e32 v145, 0xffff0000, v219
	v_cvt_pk_bf16_f32 v222, v146, v147
	v_lshlrev_b32_e32 v146, 16, v209
	v_and_b32_e32 v147, 0xffff0000, v209
	v_pk_add_f32 v[140:141], v[140:141], v[144:145]
	v_lshlrev_b32_e32 v148, 16, v207
	v_and_b32_e32 v149, 0xffff0000, v207
	v_pk_add_f32 v[142:143], v[142:143], v[146:147]
	v_cvt_pk_bf16_f32 v144, v140, v141
	v_mul_f32_e32 v141, v141, v141
	v_pk_add_f32 v[136:137], v[136:137], v[148:149]
	v_fmac_f32_e32 v141, v140, v140
	v_mul_f32_e32 v140, v143, v143
	v_lshlrev_b32_e32 v150, 16, v205
	v_and_b32_e32 v151, 0xffff0000, v205
	v_cvt_pk_bf16_f32 v145, v142, v143
	v_cvt_pk_bf16_f32 v146, v136, v137
	v_fmac_f32_e32 v140, v142, v142
	v_mul_f32_e32 v137, v137, v137
	v_pk_add_f32 v[138:139], v[138:139], v[150:151]
	v_add_f32_e32 v140, v141, v140
	v_fmac_f32_e32 v137, v136, v136
	v_add_f32_e32 v136, v137, v140
	v_mul_f32_e32 v137, v139, v139
	v_fmac_f32_e32 v137, v138, v138
	v_add_f32_e32 v136, v137, v136
	v_cvt_pk_bf16_f32 v147, v138, v139
	v_add_f32_e32 v143, v223, v136
	v_cndmask_b32_e64 v136, v222, v147, s[8:9]
	v_cndmask_b32_e64 v137, v221, v146, s[8:9]
	v_cndmask_b32_e64 v138, v220, v145, s[8:9]
	v_cndmask_b32_e64 v139, v203, v144, s[8:9]
	v_mov_b32_e32 v140, v193
	v_mov_b32_e32 v141, v193
	v_mov_b32_e32 v142, v193
	v_mov_b32_e32 v148, v193
	v_mov_b32_dpp v140, v139 row_ror:8 row_mask:0xf bank_mask:0xf
	v_mov_b32_dpp v141, v138 row_ror:8 row_mask:0xf bank_mask:0xf
	v_mov_b32_dpp v142, v137 row_ror:8 row_mask:0xf bank_mask:0xf
	v_mov_b32_dpp v148, v136 row_ror:8 row_mask:0xf bank_mask:0xf
	v_cndmask_b32_e64 v136, v140, v203, s[8:9]
	v_cndmask_b32_e64 v137, v141, v220, s[8:9]
	v_cndmask_b32_e64 v138, v142, v221, s[8:9]
	v_cndmask_b32_e64 v139, v148, v222, s[8:9]
	global_store_dwordx4 v[210:211], v[136:139], off
	ds_bpermute_b32 v136, v214, v143
	s_nop 0
	v_cndmask_b32_e64 v138, v144, v140, s[8:9]
	v_cndmask_b32_e64 v140, v146, v142, s[8:9]
	v_add_co_u32_e32 v142, vcc, 0x4000, v210
	s_waitcnt lgkmcnt(0)
	v_add_f32_e32 v136, v143, v136
	ds_bpermute_b32 v137, v215, v136
	v_cndmask_b32_e64 v139, v145, v141, s[8:9]
	v_cndmask_b32_e64 v141, v147, v148, s[8:9]
	v_addc_co_u32_e32 v143, vcc, 0, v211, vcc
	global_store_dwordx4 v[142:143], v[138:141], off
	s_and_saveexec_b64 s[44:45], s[4:5]
	s_cbranch_execz .LBB0_673
	v_ashrrev_i32_e32 v209, 31, v208
	v_lshlrev_b64 v[138:139], 6, v[208:209]
	v_lshl_add_u64 v[138:139], s[10:11], 0, v[138:139]
	v_lshl_add_u64 v[138:139], s[42:43], 2, v[138:139]
	s_lshl_b32 s14, s66, 2
	v_lshl_add_u64 v[138:139], v[138:139], 0, s[14:15]
	s_waitcnt lgkmcnt(0)
	v_add_f32_e32 v136, v136, v137
	global_store_dword v[138:139], v136, off

.LBB0_690:
	s_waitcnt vmcnt(0)
	v_readlane_b32 s71, v254, 10
	s_and_b64 vcc, exec, s[20:21]
	s_cbranch_vccz .Lna_4
	s_barrier

.LBB0_762:
	s_mul_i32 s98, s26, 0x667
	s_lshr_b32 s98, s98, 16
	s_mul_i32 s98, s98, 40
	s_sub_u32 s98, s26, s98
	s_lshr_b32 s98, s98, 3
	s_lshl_b32 s98, s98, 10
	s_add_u32 s98, s98, 0x20800
	v_mov_b32_e32 v179, v153
	v_lshl_add_u32 v179, v179, 2, s98
	ds_read_b32 v147, v179 offset:0
	ds_read_b32 v149, v179 offset:128
	ds_read_b32 v151, v179 offset:64
	ds_read_b32 v155, v179 offset:512
	ds_read_b32 v159, v179 offset:192
	ds_read_b32 v163, v179 offset:576
	ds_read_b32 v167, v179 offset:640
	ds_read_b32 v169, v179 offset:704
	s_waitcnt lgkmcnt(0)
	v_lshl_add_u32 v168, s26, 8, v153
	v_or_b32_e32 v166, 16, v168
	v_or_b32_e32 v162, 32, v168
	v_or_b32_e32 v158, 48, v168
	v_add_u32_e32 v154, 0x80, v168
	v_add_u32_e32 v150, 0x90, v168
	v_add_u32_e32 v148, 0xa0, v168
	v_add_u32_e32 v146, 0xb0, v168
	s_and_b64 vcc, exec, s[6:7]
	s_waitcnt lgkmcnt(0)
	s_waitcnt lgkmcnt(0)
	v_mov_b32_e32 v176, v147
	v_pk_mul_f32 v[124:125], v[124:125], v[176:177] op_sel_hi:[1,0]
	v_exp_f32_e64 v184, -v124
	v_exp_f32_e64 v185, -v125
	v_pk_mul_f32 v[126:127], v[126:127], v[176:177] op_sel_hi:[1,0]
	v_pk_mul_f32 v[122:123], v[122:123], v[176:177] op_sel_hi:[1,0]
	v_pk_mul_f32 v[120:121], v[120:121], v[176:177] op_sel_hi:[1,0]
	v_pk_mul_f32 v[116:117], v[116:117], v[176:177] op_sel_hi:[1,0]
	v_pk_mul_f32 v[118:119], v[118:119], v[176:177] op_sel_hi:[1,0]
	v_pk_mul_f32 v[112:113], v[112:113], v[176:177] op_sel_hi:[1,0]
	v_pk_mul_f32 v[114:115], v[114:115], v[176:177] op_sel_hi:[1,0]
	v_pk_add_f32 v[176:177], v[184:185], 1.0 op_sel_hi:[1,0]
	v_exp_f32_e64 v184, -v126
	v_exp_f32_e64 v185, -v127
	v_pk_mul_f32 v[116:117], v[124:125], v[116:117]
	v_pk_add_f32 v[124:125], v[184:185], 1.0 op_sel_hi:[1,0]
	v_rcp_f32_e32 v124, v124
	v_rcp_f32_e32 v125, v125
	v_rcp_f32_e32 v176, v176
	v_rcp_f32_e32 v177, v177
	s_waitcnt lgkmcnt(3)
	s_waitcnt lgkmcnt(2)
	v_pk_mul_f32 v[118:119], v[126:127], v[118:119]
	v_exp_f32_e64 v126, -v120
	v_exp_f32_e64 v127, -v121
	v_pk_mul_f32 v[118:119], v[118:119], v[124:125]
	v_exp_f32_e64 v124, -v122
	v_exp_f32_e64 v125, -v123
	s_waitcnt lgkmcnt(3)
	s_waitcnt lgkmcnt(2)
	v_pk_mul_f32 v[116:117], v[116:117], v[176:177]
	v_pk_mul_f32 v[114:115], v[122:123], v[114:115]
	v_cvt_pk_bf16_f32 v116, v116, v117
	v_cvt_pk_bf16_f32 v117, v118, v119
	v_pk_add_f32 v[118:119], v[126:127], 1.0 op_sel_hi:[1,0]
	v_pk_add_f32 v[122:123], v[124:125], 1.0 op_sel_hi:[1,0]
	v_rcp_f32_e32 v118, v118
	v_rcp_f32_e32 v119, v119
	s_waitcnt lgkmcnt(3)
	s_waitcnt lgkmcnt(2)
	v_rcp_f32_e32 v122, v122
	v_rcp_f32_e32 v123, v123
	s_waitcnt lgkmcnt(1)
	s_waitcnt lgkmcnt(0)
	v_mov_b32_e32 v180, v149
	v_pk_mul_f32 v[112:113], v[120:121], v[112:113]
	v_mov_b32_e32 v178, v151
	v_pk_mul_f32 v[112:113], v[112:113], v[118:119]
	v_mov_b32_e32 v164, v155
	v_lshl_add_u32 v182, s56, 7, v171
	v_cvt_pk_bf16_f32 v118, v112, v113
	v_pk_mul_f32 v[112:113], v[114:115], v[122:123]
	v_ashrrev_i32_e32 v183, 31, v182
	v_cvt_pk_bf16_f32 v119, v112, v113
	v_mov_b64_e32 v[112:113], s[24:25]
	v_mad_i64_i32 v[120:121], s[4:5], v168, s55, v[112:113]
	v_lshlrev_b64 v[114:115], 1, v[182:183]
	v_lshl_add_u64 v[120:121], v[120:121], 0, v[114:115]
	v_pk_mul_f32 v[108:109], v[108:109], v[178:179] op_sel_hi:[1,0]
	global_store_dwordx4 v[120:121], v[116:119], off
	v_pk_mul_f32 v[110:111], v[110:111], v[178:179] op_sel_hi:[1,0]
	v_pk_mul_f32 v[100:101], v[100:101], v[178:179] op_sel_hi:[1,0]
	v_exp_f32_e64 v116, -v108
	v_exp_f32_e64 v117, -v109
	v_pk_mul_f32 v[118:119], v[96:97], v[178:179] op_sel_hi:[1,0]
	v_pk_mul_f32 v[100:101], v[108:109], v[100:101]
	v_pk_mul_f32 v[102:103], v[102:103], v[178:179] op_sel_hi:[1,0]
	v_pk_add_f32 v[96:97], v[116:117], 1.0 op_sel_hi:[1,0]
	v_exp_f32_e64 v116, -v110
	v_rcp_f32_e32 v96, v96
	v_rcp_f32_e32 v97, v97
	v_exp_f32_e64 v117, -v111
	v_pk_mul_f32 v[106:107], v[106:107], v[178:179] op_sel_hi:[1,0]
	v_pk_mul_f32 v[104:105], v[104:105], v[178:179] op_sel_hi:[1,0]
	v_pk_mul_f32 v[96:97], v[100:101], v[96:97]
	v_pk_add_f32 v[100:101], v[116:117], 1.0 op_sel_hi:[1,0]
	v_pk_mul_f32 v[102:103], v[110:111], v[102:103]
	v_rcp_f32_e32 v100, v100
	v_rcp_f32_e32 v101, v101
	v_exp_f32_e64 v108, -v104
	v_exp_f32_e64 v109, -v105
	v_pk_mul_f32 v[98:99], v[98:99], v[178:179] op_sel_hi:[1,0]
	v_pk_mul_f32 v[100:101], v[102:103], v[100:101]
	v_exp_f32_e64 v102, -v106
	v_exp_f32_e64 v103, -v107
	v_cvt_pk_bf16_f32 v96, v96, v97
	v_cvt_pk_bf16_f32 v97, v100, v101
	v_pk_add_f32 v[100:101], v[108:109], 1.0 op_sel_hi:[1,0]
	v_pk_mul_f32 v[106:107], v[106:107], v[98:99]
	v_pk_add_f32 v[98:99], v[102:103], 1.0 op_sel_hi:[1,0]
	v_rcp_f32_e32 v100, v100
	v_rcp_f32_e32 v101, v101
	v_rcp_f32_e32 v102, v98
	v_rcp_f32_e32 v103, v99
	v_pk_mul_f32 v[98:99], v[104:105], v[118:119]
	v_pk_mul_f32 v[92:93], v[92:93], v[180:181] op_sel_hi:[1,0]
	v_pk_mul_f32 v[98:99], v[98:99], v[100:101]
	v_pk_mul_f32 v[100:101], v[106:107], v[102:103]
	v_cvt_pk_bf16_f32 v98, v98, v99
	v_pk_mul_f32 v[94:95], v[94:95], v[180:181] op_sel_hi:[1,0]
	v_cvt_pk_bf16_f32 v99, v100, v101
	v_mad_i64_i32 v[100:101], s[4:5], v166, s55, v[112:113]
	v_lshl_add_u64 v[100:101], v[100:101], 0, v[114:115]
	global_store_dwordx4 v[100:101], v[96:99], off
	v_pk_mul_f32 v[84:85], v[84:85], v[180:181] op_sel_hi:[1,0]
	v_pk_mul_f32 v[86:87], v[86:87], v[180:181] op_sel_hi:[1,0]
	v_exp_f32_e64 v96, -v92
	v_exp_f32_e64 v97, -v93
	v_pk_mul_f32 v[98:99], v[80:81], v[180:181] op_sel_hi:[1,0]
	v_pk_mul_f32 v[84:85], v[92:93], v[84:85]
	v_pk_mul_f32 v[90:91], v[90:91], v[180:181] op_sel_hi:[1,0]
	v_pk_add_f32 v[80:81], v[96:97], 1.0 op_sel_hi:[1,0]
	v_exp_f32_e64 v96, -v94
	v_rcp_f32_e32 v80, v80
	v_rcp_f32_e32 v81, v81
	v_exp_f32_e64 v97, -v95
	v_pk_mul_f32 v[88:89], v[88:89], v[180:181] op_sel_hi:[1,0]
	v_pk_mul_f32 v[86:87], v[94:95], v[86:87]
	v_pk_mul_f32 v[80:81], v[84:85], v[80:81]
	v_pk_add_f32 v[84:85], v[96:97], 1.0 op_sel_hi:[1,0]
	v_exp_f32_e64 v92, -v88
	v_rcp_f32_e32 v84, v84
	v_rcp_f32_e32 v85, v85
	v_exp_f32_e64 v93, -v89
	v_pk_mul_f32 v[82:83], v[82:83], v[180:181] op_sel_hi:[1,0]
	v_cvt_pk_bf16_f32 v80, v80, v81
	v_pk_mul_f32 v[84:85], v[86:87], v[84:85]
	v_exp_f32_e64 v86, -v90
	v_exp_f32_e64 v87, -v91
	v_cvt_pk_bf16_f32 v81, v84, v85
	v_pk_add_f32 v[84:85], v[92:93], 1.0 op_sel_hi:[1,0]
	v_pk_mul_f32 v[90:91], v[90:91], v[82:83]
	v_pk_add_f32 v[82:83], v[86:87], 1.0 op_sel_hi:[1,0]
	v_rcp_f32_e32 v84, v84
	v_rcp_f32_e32 v85, v85
	v_rcp_f32_e32 v86, v82
	v_rcp_f32_e32 v87, v83
	v_mov_b32_e32 v170, v159
	v_pk_mul_f32 v[82:83], v[88:89], v[98:99]
	v_pk_mul_f32 v[60:61], v[60:61], v[164:165] op_sel_hi:[1,0]
	v_pk_mul_f32 v[82:83], v[82:83], v[84:85]
	v_pk_mul_f32 v[84:85], v[90:91], v[86:87]
	v_cvt_pk_bf16_f32 v82, v82, v83
	v_pk_mul_f32 v[76:77], v[76:77], v[170:171] op_sel_hi:[1,0]
	v_cvt_pk_bf16_f32 v83, v84, v85
	v_mad_i64_i32 v[84:85], s[4:5], v162, s55, v[112:113]
	v_lshl_add_u64 v[84:85], v[84:85], 0, v[114:115]
	global_store_dwordx4 v[84:85], v[80:83], off
	v_pk_mul_f32 v[78:79], v[78:79], v[170:171] op_sel_hi:[1,0]
	v_pk_mul_f32 v[68:69], v[68:69], v[170:171] op_sel_hi:[1,0]
	v_exp_f32_e64 v80, -v76
	v_exp_f32_e64 v81, -v77
	v_pk_mul_f32 v[82:83], v[64:65], v[170:171] op_sel_hi:[1,0]
	v_pk_mul_f32 v[68:69], v[76:77], v[68:69]
	v_pk_mul_f32 v[70:71], v[70:71], v[170:171] op_sel_hi:[1,0]
	v_pk_add_f32 v[64:65], v[80:81], 1.0 op_sel_hi:[1,0]
	v_exp_f32_e64 v80, -v78
	v_rcp_f32_e32 v64, v64
	v_rcp_f32_e32 v65, v65
	v_exp_f32_e64 v81, -v79
	v_pk_mul_f32 v[74:75], v[74:75], v[170:171] op_sel_hi:[1,0]
	v_pk_mul_f32 v[72:73], v[72:73], v[170:171] op_sel_hi:[1,0]
	v_pk_mul_f32 v[64:65], v[68:69], v[64:65]
	v_pk_add_f32 v[68:69], v[80:81], 1.0 op_sel_hi:[1,0]
	v_pk_mul_f32 v[70:71], v[78:79], v[70:71]
	v_rcp_f32_e32 v68, v68
	v_rcp_f32_e32 v69, v69
	v_exp_f32_e64 v76, -v72
	v_exp_f32_e64 v77, -v73
	v_pk_mul_f32 v[66:67], v[66:67], v[170:171] op_sel_hi:[1,0]
	v_pk_mul_f32 v[68:69], v[70:71], v[68:69]
	v_exp_f32_e64 v70, -v74
	v_exp_f32_e64 v71, -v75
	v_cvt_pk_bf16_f32 v64, v64, v65
	v_cvt_pk_bf16_f32 v65, v68, v69
	v_pk_add_f32 v[68:69], v[76:77], 1.0 op_sel_hi:[1,0]
	v_pk_mul_f32 v[74:75], v[74:75], v[66:67]
	v_pk_add_f32 v[66:67], v[70:71], 1.0 op_sel_hi:[1,0]
	v_rcp_f32_e32 v68, v68
	v_rcp_f32_e32 v69, v69
	v_rcp_f32_e32 v70, v66
	v_rcp_f32_e32 v71, v67
	v_pk_mul_f32 v[66:67], v[72:73], v[82:83]
	v_pk_mul_f32 v[62:63], v[62:63], v[164:165] op_sel_hi:[1,0]
	v_pk_mul_f32 v[66:67], v[66:67], v[68:69]
	v_pk_mul_f32 v[68:69], v[74:75], v[70:71]
	v_cvt_pk_bf16_f32 v66, v66, v67
	v_pk_mul_f32 v[52:53], v[52:53], v[164:165] op_sel_hi:[1,0]
	v_cvt_pk_bf16_f32 v67, v68, v69
	v_mad_i64_i32 v[68:69], s[4:5], v158, s55, v[112:113]
	v_lshl_add_u64 v[68:69], v[68:69], 0, v[114:115]
	global_store_dwordx4 v[68:69], v[64:67], off
	v_pk_mul_f32 v[52:53], v[60:61], v[52:53]
	v_exp_f32_e64 v64, -v60
	v_exp_f32_e64 v65, -v61
	v_pk_mul_f32 v[66:67], v[48:49], v[164:165] op_sel_hi:[1,0]
	v_pk_mul_f32 v[54:55], v[54:55], v[164:165] op_sel_hi:[1,0]
	s_waitcnt lgkmcnt(0)
	v_pk_add_f32 v[48:49], v[64:65], 1.0 op_sel_hi:[1,0]
	v_exp_f32_e64 v64, -v62
	v_rcp_f32_e32 v48, v48
	v_rcp_f32_e32 v49, v49
	v_exp_f32_e64 v65, -v63
	v_pk_mul_f32 v[58:59], v[58:59], v[164:165] op_sel_hi:[1,0]
	v_pk_mul_f32 v[56:57], v[56:57], v[164:165] op_sel_hi:[1,0]
	v_pk_mul_f32 v[48:49], v[52:53], v[48:49]
	v_pk_add_f32 v[52:53], v[64:65], 1.0 op_sel_hi:[1,0]
	v_pk_mul_f32 v[54:55], v[62:63], v[54:55]
	v_rcp_f32_e32 v52, v52
	v_rcp_f32_e32 v53, v53
	v_exp_f32_e64 v60, -v56
	v_exp_f32_e64 v61, -v57
	v_pk_mul_f32 v[52:53], v[54:55], v[52:53]
	v_exp_f32_e64 v54, -v58
	v_exp_f32_e64 v55, -v59
	v_pk_mul_f32 v[50:51], v[50:51], v[164:165] op_sel_hi:[1,0]
	v_cvt_pk_bf16_f32 v48, v48, v49
	v_cvt_pk_bf16_f32 v49, v52, v53
	v_pk_add_f32 v[52:53], v[60:61], 1.0 op_sel_hi:[1,0]
	v_pk_mul_f32 v[58:59], v[58:59], v[50:51]
	v_pk_add_f32 v[50:51], v[54:55], 1.0 op_sel_hi:[1,0]
	s_waitcnt lgkmcnt(0)
	v_rcp_f32_e32 v52, v52
	v_rcp_f32_e32 v53, v53
	v_rcp_f32_e32 v54, v50
	v_rcp_f32_e32 v55, v51
	v_mov_b32_e32 v160, v163
	v_pk_mul_f32 v[50:51], v[56:57], v[66:67]
	v_pk_mul_f32 v[50:51], v[50:51], v[52:53]
	v_pk_mul_f32 v[52:53], v[58:59], v[54:55]
	v_cvt_pk_bf16_f32 v50, v50, v51
	v_pk_mul_f32 v[44:45], v[44:45], v[160:161] op_sel_hi:[1,0]
	v_cvt_pk_bf16_f32 v51, v52, v53
	v_mad_i64_i32 v[52:53], s[4:5], v154, s55, v[112:113]
	v_lshl_add_u64 v[52:53], v[52:53], 0, v[114:115]
	global_store_dwordx4 v[52:53], v[48:51], off
	v_pk_mul_f32 v[46:47], v[46:47], v[160:161] op_sel_hi:[1,0]
	v_pk_mul_f32 v[36:37], v[36:37], v[160:161] op_sel_hi:[1,0]
	v_exp_f32_e64 v48, -v44
	v_exp_f32_e64 v49, -v45
	v_pk_mul_f32 v[50:51], v[32:33], v[160:161] op_sel_hi:[1,0]
	v_pk_mul_f32 v[36:37], v[44:45], v[36:37]
	v_pk_mul_f32 v[38:39], v[38:39], v[160:161] op_sel_hi:[1,0]
	v_pk_add_f32 v[32:33], v[48:49], 1.0 op_sel_hi:[1,0]
	v_exp_f32_e64 v48, -v46
	v_rcp_f32_e32 v32, v32
	v_rcp_f32_e32 v33, v33
	v_exp_f32_e64 v49, -v47
	s_waitcnt lgkmcnt(0)
	v_pk_mul_f32 v[42:43], v[42:43], v[160:161] op_sel_hi:[1,0]
	v_pk_mul_f32 v[32:33], v[36:37], v[32:33]
	v_pk_add_f32 v[36:37], v[48:49], 1.0 op_sel_hi:[1,0]
	v_pk_mul_f32 v[40:41], v[40:41], v[160:161] op_sel_hi:[1,0]
	v_rcp_f32_e32 v36, v36
	v_rcp_f32_e32 v37, v37
	v_pk_mul_f32 v[38:39], v[46:47], v[38:39]
	v_exp_f32_e64 v44, -v40
	v_exp_f32_e64 v45, -v41
	v_pk_mul_f32 v[36:37], v[38:39], v[36:37]
	v_exp_f32_e64 v38, -v42
	v_exp_f32_e64 v39, -v43
	v_pk_mul_f32 v[34:35], v[34:35], v[160:161] op_sel_hi:[1,0]
	v_cvt_pk_bf16_f32 v32, v32, v33
	v_cvt_pk_bf16_f32 v33, v36, v37
	v_pk_add_f32 v[36:37], v[44:45], 1.0 op_sel_hi:[1,0]
	v_pk_mul_f32 v[42:43], v[42:43], v[34:35]
	v_pk_add_f32 v[34:35], v[38:39], 1.0 op_sel_hi:[1,0]
	s_waitcnt lgkmcnt(0)
	v_rcp_f32_e32 v36, v36
	v_rcp_f32_e32 v37, v37
	v_rcp_f32_e32 v38, v34
	v_rcp_f32_e32 v39, v35
	v_mov_b32_e32 v156, v167
	v_pk_mul_f32 v[34:35], v[40:41], v[50:51]
	v_pk_mul_f32 v[34:35], v[34:35], v[36:37]
	v_pk_mul_f32 v[36:37], v[42:43], v[38:39]
	v_cvt_pk_bf16_f32 v34, v34, v35
	v_pk_mul_f32 v[28:29], v[28:29], v[156:157] op_sel_hi:[1,0]
	v_cvt_pk_bf16_f32 v35, v36, v37
	v_mad_i64_i32 v[36:37], s[4:5], v150, s55, v[112:113]
	v_lshl_add_u64 v[36:37], v[36:37], 0, v[114:115]
	global_store_dwordx4 v[36:37], v[32:35], off
	v_pk_mul_f32 v[30:31], v[30:31], v[156:157] op_sel_hi:[1,0]
	v_pk_mul_f32 v[20:21], v[20:21], v[156:157] op_sel_hi:[1,0]
	v_exp_f32_e64 v32, -v28
	v_exp_f32_e64 v33, -v29
	v_pk_mul_f32 v[34:35], v[16:17], v[156:157] op_sel_hi:[1,0]
	v_pk_mul_f32 v[20:21], v[28:29], v[20:21]
	v_pk_mul_f32 v[22:23], v[22:23], v[156:157] op_sel_hi:[1,0]
	v_pk_add_f32 v[16:17], v[32:33], 1.0 op_sel_hi:[1,0]
	v_exp_f32_e64 v32, -v30
	v_rcp_f32_e32 v16, v16
	v_rcp_f32_e32 v17, v17
	v_exp_f32_e64 v33, -v31
	s_waitcnt lgkmcnt(0)
	v_pk_mul_f32 v[26:27], v[26:27], v[156:157] op_sel_hi:[1,0]
	v_pk_mul_f32 v[16:17], v[20:21], v[16:17]
	v_pk_add_f32 v[20:21], v[32:33], 1.0 op_sel_hi:[1,0]
	v_pk_mul_f32 v[24:25], v[24:25], v[156:157] op_sel_hi:[1,0]
	v_rcp_f32_e32 v20, v20
	v_rcp_f32_e32 v21, v21
	v_pk_mul_f32 v[22:23], v[30:31], v[22:23]
	v_exp_f32_e64 v28, -v24
	v_exp_f32_e64 v29, -v25
	v_pk_mul_f32 v[20:21], v[22:23], v[20:21]
	v_exp_f32_e64 v22, -v26
	v_exp_f32_e64 v23, -v27
	v_pk_mul_f32 v[18:19], v[18:19], v[156:157] op_sel_hi:[1,0]
	v_cvt_pk_bf16_f32 v16, v16, v17
	v_cvt_pk_bf16_f32 v17, v20, v21
	v_pk_add_f32 v[20:21], v[28:29], 1.0 op_sel_hi:[1,0]
	v_pk_mul_f32 v[26:27], v[26:27], v[18:19]
	v_pk_add_f32 v[18:19], v[22:23], 1.0 op_sel_hi:[1,0]
	s_waitcnt lgkmcnt(0)
	v_rcp_f32_e32 v20, v20
	v_rcp_f32_e32 v21, v21
	v_rcp_f32_e32 v22, v18
	v_rcp_f32_e32 v23, v19
	v_mov_b32_e32 v152, v169
	v_pk_mul_f32 v[18:19], v[24:25], v[34:35]
	v_pk_mul_f32 v[12:13], v[12:13], v[152:153] op_sel_hi:[1,0]
	v_pk_mul_f32 v[18:19], v[18:19], v[20:21]
	v_pk_mul_f32 v[20:21], v[26:27], v[22:23]
	v_cvt_pk_bf16_f32 v18, v18, v19
	v_pk_mul_f32 v[14:15], v[14:15], v[152:153] op_sel_hi:[1,0]
	v_cvt_pk_bf16_f32 v19, v20, v21
	v_mad_i64_i32 v[20:21], s[4:5], v148, s55, v[112:113]
	v_lshl_add_u64 v[20:21], v[20:21], 0, v[114:115]
	global_store_dwordx4 v[20:21], v[16:19], off
	v_pk_mul_f32 v[4:5], v[4:5], v[152:153] op_sel_hi:[1,0]
	v_pk_mul_f32 v[6:7], v[6:7], v[152:153] op_sel_hi:[1,0]
	v_exp_f32_e64 v16, -v12
	v_exp_f32_e64 v17, -v13
	v_pk_mul_f32 v[18:19], v[0:1], v[152:153] op_sel_hi:[1,0]
	v_pk_mul_f32 v[4:5], v[12:13], v[4:5]
	v_pk_mul_f32 v[10:11], v[10:11], v[152:153] op_sel_hi:[1,0]
	v_pk_add_f32 v[0:1], v[16:17], 1.0 op_sel_hi:[1,0]
	v_exp_f32_e64 v16, -v14
	v_rcp_f32_e32 v0, v0
	v_rcp_f32_e32 v1, v1
	v_exp_f32_e64 v17, -v15
	v_pk_mul_f32 v[8:9], v[8:9], v[152:153] op_sel_hi:[1,0]
	v_pk_mul_f32 v[6:7], v[14:15], v[6:7]
	v_pk_mul_f32 v[0:1], v[4:5], v[0:1]
	v_pk_add_f32 v[4:5], v[16:17], 1.0 op_sel_hi:[1,0]
	v_exp_f32_e64 v12, -v8
	v_rcp_f32_e32 v4, v4
	v_rcp_f32_e32 v5, v5
	v_exp_f32_e64 v13, -v9
	v_pk_mul_f32 v[2:3], v[2:3], v[152:153] op_sel_hi:[1,0]
	v_cvt_pk_bf16_f32 v0, v0, v1
	v_pk_mul_f32 v[4:5], v[6:7], v[4:5]
	v_exp_f32_e64 v6, -v10
	v_exp_f32_e64 v7, -v11
	v_cvt_pk_bf16_f32 v1, v4, v5
	v_pk_add_f32 v[4:5], v[12:13], 1.0 op_sel_hi:[1,0]
	v_pk_mul_f32 v[10:11], v[10:11], v[2:3]
	v_pk_add_f32 v[2:3], v[6:7], 1.0 op_sel_hi:[1,0]
	v_rcp_f32_e32 v4, v4
	v_rcp_f32_e32 v5, v5
	v_rcp_f32_e32 v6, v2
	v_rcp_f32_e32 v7, v3
	v_pk_mul_f32 v[2:3], v[8:9], v[18:19]
	s_nop 0
	v_pk_mul_f32 v[2:3], v[2:3], v[4:5]
	v_pk_mul_f32 v[4:5], v[10:11], v[6:7]
	v_cvt_pk_bf16_f32 v2, v2, v3
	s_nop 0
	v_cvt_pk_bf16_f32 v3, v4, v5
	v_mad_i64_i32 v[4:5], s[4:5], v146, s55, v[112:113]
	v_lshl_add_u64 v[4:5], v[4:5], 0, v[114:115]
	s_mov_b64 s[4:5], -1
	global_store_dwordx4 v[4:5], v[0:3], off
	s_cbranch_vccnz .LBB0_753
	s_andn2_b64 vcc, exec, s[12:13]
	s_cbranch_vccnz .LBB0_752
	s_branch .LBB0_752
.LBB0_765:
	s_waitcnt vmcnt(0)
	s_and_b64 vcc, exec, s[16:17]
	s_cbranch_vccz .Lna_5
	s_barrier

.LBB0_842:
	s_waitcnt vmcnt(0)
	v_readlane_b32 s71, v254, 10
	s_and_b64 vcc, exec, s[16:17]
	s_cbranch_vccz .Lna_6
	s_barrier
